# P3 v7: same as v6 but LDS-DMA for step n+2 issued at the very start of step n (more prefetch distance)
# baseline (speedup 1.0000x reference)
.Lp3O_loop:
	s_add_i32 m0, s46, 0x14000
	s_nop 0
	global_load_lds_dwordx4 v255, s[8:9]
	s_add_i32 m0, s46, 0x14400
	s_nop 0
	global_load_lds_dwordx4 v254, s[8:9]
	s_add_i32 m0, s47, 0x14000
	s_nop 0
	global_load_lds_dwordx4 v253, s[10:11]
	s_add_i32 m0, s48, 0x14000
	s_nop 0
	global_load_lds_dwordx4 v252, s[12:13]
	s_add_i32 m0, s48, 0x14400
	s_nop 0
	global_load_lds_dwordx4 v251, s[12:13]
	s_cmp_lt_u32 s33, 29
	s_cselect_b32 s43, 0x10000, 0
	s_add_u32 s8, s8, s43
	s_addc_u32 s9, s9, 0
	s_cmp_lt_u32 s33, 29
	s_cselect_b32 s43, 0x2000, 0
	s_add_u32 s10, s10, s43
	s_addc_u32 s11, s11, 0
	s_cmp_lt_u32 s33, 29
	s_cselect_b32 s43, 0x4000, 0
	s_add_u32 s12, s12, s43
	s_addc_u32 s13, s13, 0
	ds_read_b128 v[60:63], v241 offset:0
	ds_read_b128 v[12:15], v223 offset:0
	ds_read_b128 v[16:19], v223 offset:4096
	ds_read_b128 v[64:67], v241 offset:4096
	ds_read_b128 v[68:71], v240 offset:0
	ds_read_b128 v[20:23], v222 offset:0
	ds_read_b128 v[24:27], v222 offset:4096
	ds_read_b128 v[72:75], v240 offset:4096
	ds_read_b128 v[76:79], v239 offset:0
	ds_read_b128 v[28:31], v221 offset:0
	ds_read_b128 v[32:35], v221 offset:4096
	ds_read_b128 v[80:83], v239 offset:4096
	s_waitcnt lgkmcnt(8)
	v_mfma_f32_16x16x32_bf16 v[108:111], v[12:15], v[60:63], 0
	v_mfma_f32_16x16x32_bf16 v[112:115], v[16:19], v[60:63], 0
	v_mfma_f32_16x16x32_bf16 v[116:119], v[12:15], v[64:67], 0
	v_mfma_f32_16x16x32_bf16 v[120:123], v[16:19], v[64:67], 0
	ds_read_b128 v[84:87], v238 offset:0
	ds_read_b128 v[36:39], v220 offset:0
	ds_read_b128 v[40:43], v220 offset:4096
	ds_read_b128 v[88:91], v238 offset:4096
	s_waitcnt lgkmcnt(8)
	v_mfma_f32_16x16x32_bf16 v[108:111], v[20:23], v[68:71], v[108:111]
	v_mfma_f32_16x16x32_bf16 v[112:115], v[24:27], v[68:71], v[112:115]
	v_mfma_f32_16x16x32_bf16 v[116:119], v[20:23], v[72:75], v[116:119]
	v_mfma_f32_16x16x32_bf16 v[120:123], v[24:27], v[72:75], v[120:123]
	ds_read_b128 v[92:95], v231 offset:0
	ds_read_b128 v[44:47], v219 offset:0
	ds_read_b128 v[48:51], v219 offset:2048
	ds_read_b128 v[96:99], v231 offset:2048
	s_waitcnt lgkmcnt(8)
	v_mfma_f32_16x16x32_bf16 v[108:111], v[28:31], v[76:79], v[108:111]
	v_mfma_f32_16x16x32_bf16 v[112:115], v[32:35], v[76:79], v[112:115]
	v_mfma_f32_16x16x32_bf16 v[116:119], v[28:31], v[80:83], v[116:119]
	v_mfma_f32_16x16x32_bf16 v[120:123], v[32:35], v[80:83], v[120:123]
	ds_read_b128 v[100:103], v230 offset:0
	ds_read_b128 v[52:55], v218 offset:0
	ds_read_b128 v[56:59], v218 offset:2048
	ds_read_b128 v[104:107], v230 offset:2048
	s_waitcnt lgkmcnt(8)
	v_mfma_f32_16x16x32_bf16 v[108:111], v[36:39], v[84:87], v[108:111]
	v_mfma_f32_16x16x32_bf16 v[112:115], v[40:43], v[84:87], v[112:115]
	v_mfma_f32_16x16x32_bf16 v[116:119], v[36:39], v[88:91], v[116:119]
	v_mfma_f32_16x16x32_bf16 v[120:123], v[40:43], v[88:91], v[120:123]
	s_waitcnt lgkmcnt(4)
	v_mfma_f32_16x16x32_bf16 v[108:111], v[44:47], v[92:95], v[108:111]
	v_mfma_f32_16x16x32_bf16 v[112:115], v[48:51], v[92:95], v[112:115]
	v_mfma_f32_16x16x32_bf16 v[116:119], v[44:47], v[96:99], v[116:119]
	v_mfma_f32_16x16x32_bf16 v[120:123], v[48:51], v[96:99], v[120:123]
	s_waitcnt lgkmcnt(0)
	v_mfma_f32_16x16x32_bf16 v[108:111], v[52:55], v[100:103], v[108:111]
	v_mfma_f32_16x16x32_bf16 v[112:115], v[56:59], v[100:103], v[112:115]
	v_mfma_f32_16x16x32_bf16 v[116:119], v[52:55], v[104:107], v[116:119]
	v_mfma_f32_16x16x32_bf16 v[120:123], v[56:59], v[104:107], v[120:123]
	s_nop 7
	s_nop 7
	v_cvt_pk_bf16_f32 v124, v108, v109
	v_cvt_pk_bf16_f32 v125, v110, v111
	v_cvt_pk_bf16_f32 v126, v112, v113
	v_cvt_pk_bf16_f32 v127, v114, v115
	v_cvt_pk_bf16_f32 v128, v116, v117
	v_cvt_pk_bf16_f32 v129, v118, v119
	v_cvt_pk_bf16_f32 v130, v120, v121
	v_cvt_pk_bf16_f32 v131, v122, v123
	global_store_dwordx2 v248, v[124:125], s[18:19]
	global_store_dwordx2 v248, v[126:127], s[18:19] offset:32
	global_store_dwordx2 v247, v[128:129], s[18:19]
	global_store_dwordx2 v247, v[130:131], s[18:19] offset:32
	s_add_u32 s18, s18, 0x20000
	s_addc_u32 s19, s19, 0
	s_add_i32 s33, s33, 1
	s_waitcnt vmcnt(13)
	s_waitcnt lgkmcnt(0)
	s_barrier
	s_mov_b32 m0, s46
	s_nop 0
	global_load_lds_dwordx4 v255, s[8:9]
	s_add_i32 m0, s46, 0x400
	s_nop 0
	global_load_lds_dwordx4 v254, s[8:9]
	s_mov_b32 m0, s47
	s_nop 0
	global_load_lds_dwordx4 v253, s[10:11]
	s_mov_b32 m0, s48
	s_nop 0
	global_load_lds_dwordx4 v252, s[12:13]
	s_add_i32 m0, s48, 0x400
	s_nop 0
	global_load_lds_dwordx4 v251, s[12:13]
	s_cmp_lt_u32 s33, 29
	s_cselect_b32 s43, 0x10000, 0
	s_add_u32 s8, s8, s43
	s_addc_u32 s9, s9, 0
	s_cmp_lt_u32 s33, 29
	s_cselect_b32 s43, 0x2000, 0
	s_add_u32 s10, s10, s43
	s_addc_u32 s11, s11, 0
	s_cmp_lt_u32 s33, 29
	s_cselect_b32 s43, 0x4000, 0
	s_add_u32 s12, s12, s43
	s_addc_u32 s13, s13, 0
	ds_read_b128 v[60:63], v241 offset:40960
	ds_read_b128 v[12:15], v223 offset:12544
	ds_read_b128 v[16:19], v223 offset:16640
	ds_read_b128 v[64:67], v241 offset:45056
	ds_read_b128 v[68:71], v240 offset:40960
	ds_read_b128 v[20:23], v222 offset:12544
	ds_read_b128 v[24:27], v222 offset:16640
	ds_read_b128 v[72:75], v240 offset:45056
	ds_read_b128 v[76:79], v239 offset:40960
	ds_read_b128 v[28:31], v221 offset:12544
	ds_read_b128 v[32:35], v221 offset:16640
	ds_read_b128 v[80:83], v239 offset:45056
	s_waitcnt lgkmcnt(8)
	v_mfma_f32_16x16x32_bf16 v[108:111], v[12:15], v[60:63], 0
	v_mfma_f32_16x16x32_bf16 v[112:115], v[16:19], v[60:63], 0
	v_mfma_f32_16x16x32_bf16 v[116:119], v[12:15], v[64:67], 0
	v_mfma_f32_16x16x32_bf16 v[120:123], v[16:19], v[64:67], 0
	ds_read_b128 v[84:87], v238 offset:40960
	ds_read_b128 v[36:39], v220 offset:12544
	ds_read_b128 v[40:43], v220 offset:16640
	ds_read_b128 v[88:91], v238 offset:45056
	s_waitcnt lgkmcnt(8)
	v_mfma_f32_16x16x32_bf16 v[108:111], v[20:23], v[68:71], v[108:111]
	v_mfma_f32_16x16x32_bf16 v[112:115], v[24:27], v[68:71], v[112:115]
	v_mfma_f32_16x16x32_bf16 v[116:119], v[20:23], v[72:75], v[116:119]
	v_mfma_f32_16x16x32_bf16 v[120:123], v[24:27], v[72:75], v[120:123]
	ds_read_b128 v[92:95], v231 offset:40960
	ds_read_b128 v[44:47], v219 offset:12288
	ds_read_b128 v[48:51], v219 offset:14336
	ds_read_b128 v[96:99], v231 offset:43008
	s_waitcnt lgkmcnt(8)
	v_mfma_f32_16x16x32_bf16 v[108:111], v[28:31], v[76:79], v[108:111]
	v_mfma_f32_16x16x32_bf16 v[112:115], v[32:35], v[76:79], v[112:115]
	v_mfma_f32_16x16x32_bf16 v[116:119], v[28:31], v[80:83], v[116:119]
	v_mfma_f32_16x16x32_bf16 v[120:123], v[32:35], v[80:83], v[120:123]
	ds_read_b128 v[100:103], v230 offset:40960
	ds_read_b128 v[52:55], v218 offset:12288
	ds_read_b128 v[56:59], v218 offset:14336
	ds_read_b128 v[104:107], v230 offset:43008
	s_waitcnt lgkmcnt(8)
	v_mfma_f32_16x16x32_bf16 v[108:111], v[36:39], v[84:87], v[108:111]
	v_mfma_f32_16x16x32_bf16 v[112:115], v[40:43], v[84:87], v[112:115]
	v_mfma_f32_16x16x32_bf16 v[116:119], v[36:39], v[88:91], v[116:119]
	v_mfma_f32_16x16x32_bf16 v[120:123], v[40:43], v[88:91], v[120:123]
	s_waitcnt lgkmcnt(4)
	v_mfma_f32_16x16x32_bf16 v[108:111], v[44:47], v[92:95], v[108:111]
	v_mfma_f32_16x16x32_bf16 v[112:115], v[48:51], v[92:95], v[112:115]
	v_mfma_f32_16x16x32_bf16 v[116:119], v[44:47], v[96:99], v[116:119]
	v_mfma_f32_16x16x32_bf16 v[120:123], v[48:51], v[96:99], v[120:123]
	s_waitcnt lgkmcnt(0)
	v_mfma_f32_16x16x32_bf16 v[108:111], v[52:55], v[100:103], v[108:111]
	v_mfma_f32_16x16x32_bf16 v[112:115], v[56:59], v[100:103], v[112:115]
	v_mfma_f32_16x16x32_bf16 v[116:119], v[52:55], v[104:107], v[116:119]
	v_mfma_f32_16x16x32_bf16 v[120:123], v[56:59], v[104:107], v[120:123]
	s_nop 7
	s_nop 7
	v_cvt_pk_bf16_f32 v124, v108, v109
	v_cvt_pk_bf16_f32 v125, v110, v111
	v_cvt_pk_bf16_f32 v126, v112, v113
	v_cvt_pk_bf16_f32 v127, v114, v115
	v_cvt_pk_bf16_f32 v128, v116, v117
	v_cvt_pk_bf16_f32 v129, v118, v119
	v_cvt_pk_bf16_f32 v130, v120, v121
	v_cvt_pk_bf16_f32 v131, v122, v123
	global_store_dwordx2 v248, v[124:125], s[18:19]
	global_store_dwordx2 v248, v[126:127], s[18:19] offset:32
	global_store_dwordx2 v247, v[128:129], s[18:19]
	global_store_dwordx2 v247, v[130:131], s[18:19] offset:32
	s_add_u32 s18, s18, 0x20000
	s_addc_u32 s19, s19, 0
	s_add_i32 s33, s33, 1
	s_waitcnt vmcnt(13)
	s_waitcnt lgkmcnt(0)
	s_barrier
	s_add_i32 m0, s46, 0xa000
	s_nop 0
	global_load_lds_dwordx4 v255, s[8:9]
	s_add_i32 m0, s46, 0xa400
	s_nop 0
	global_load_lds_dwordx4 v254, s[8:9]
	s_add_i32 m0, s47, 0xa000
	s_nop 0
	global_load_lds_dwordx4 v253, s[10:11]
	s_add_i32 m0, s48, 0xa000
	s_nop 0
	global_load_lds_dwordx4 v252, s[12:13]
	s_add_i32 m0, s48, 0xa400
	s_nop 0
	global_load_lds_dwordx4 v251, s[12:13]
	s_cmp_lt_u32 s33, 29
	s_cselect_b32 s43, 0x10000, 0
	s_add_u32 s8, s8, s43
	s_addc_u32 s9, s9, 0
	s_cmp_lt_u32 s33, 29
	s_cselect_b32 s43, 0x2000, 0
	s_add_u32 s10, s10, s43
	s_addc_u32 s11, s11, 0
	s_cmp_lt_u32 s33, 29
	s_cselect_b32 s43, 0x4000, 0
	s_add_u32 s12, s12, s43
	s_addc_u32 s13, s13, 0
	ds_read_b128 v[60:63], v235 offset:0
	ds_read_b128 v[12:15], v223 offset:0
	ds_read_b128 v[16:19], v223 offset:4096
	ds_read_b128 v[64:67], v235 offset:4096
	ds_read_b128 v[68:71], v234 offset:0
	ds_read_b128 v[20:23], v222 offset:0
	ds_read_b128 v[24:27], v222 offset:4096
	ds_read_b128 v[72:75], v234 offset:4096
	ds_read_b128 v[76:79], v233 offset:0
	ds_read_b128 v[28:31], v221 offset:0
	ds_read_b128 v[32:35], v221 offset:4096
	ds_read_b128 v[80:83], v233 offset:4096
	s_waitcnt lgkmcnt(8)
	v_mfma_f32_16x16x32_bf16 v[108:111], v[12:15], v[60:63], 0
	v_mfma_f32_16x16x32_bf16 v[112:115], v[16:19], v[60:63], 0
	v_mfma_f32_16x16x32_bf16 v[116:119], v[12:15], v[64:67], 0
	v_mfma_f32_16x16x32_bf16 v[120:123], v[16:19], v[64:67], 0
	ds_read_b128 v[84:87], v232 offset:0
	ds_read_b128 v[36:39], v220 offset:0
	ds_read_b128 v[40:43], v220 offset:4096
	ds_read_b128 v[88:91], v232 offset:4096
	s_waitcnt lgkmcnt(8)
	v_mfma_f32_16x16x32_bf16 v[108:111], v[20:23], v[68:71], v[108:111]
	v_mfma_f32_16x16x32_bf16 v[112:115], v[24:27], v[68:71], v[112:115]
	v_mfma_f32_16x16x32_bf16 v[116:119], v[20:23], v[72:75], v[116:119]
	v_mfma_f32_16x16x32_bf16 v[120:123], v[24:27], v[72:75], v[120:123]
	ds_read_b128 v[92:95], v229 offset:0
	ds_read_b128 v[44:47], v219 offset:0
	ds_read_b128 v[48:51], v219 offset:2048
	ds_read_b128 v[96:99], v229 offset:2048
	s_waitcnt lgkmcnt(8)
	v_mfma_f32_16x16x32_bf16 v[108:111], v[28:31], v[76:79], v[108:111]
	v_mfma_f32_16x16x32_bf16 v[112:115], v[32:35], v[76:79], v[112:115]
	v_mfma_f32_16x16x32_bf16 v[116:119], v[28:31], v[80:83], v[116:119]
	v_mfma_f32_16x16x32_bf16 v[120:123], v[32:35], v[80:83], v[120:123]
	ds_read_b128 v[100:103], v228 offset:0
	ds_read_b128 v[52:55], v218 offset:0
	ds_read_b128 v[56:59], v218 offset:2048
	ds_read_b128 v[104:107], v228 offset:2048
	s_waitcnt lgkmcnt(8)
	v_mfma_f32_16x16x32_bf16 v[108:111], v[36:39], v[84:87], v[108:111]
	v_mfma_f32_16x16x32_bf16 v[112:115], v[40:43], v[84:87], v[112:115]
	v_mfma_f32_16x16x32_bf16 v[116:119], v[36:39], v[88:91], v[116:119]
	v_mfma_f32_16x16x32_bf16 v[120:123], v[40:43], v[88:91], v[120:123]
	s_waitcnt lgkmcnt(4)
	v_mfma_f32_16x16x32_bf16 v[108:111], v[44:47], v[92:95], v[108:111]
	v_mfma_f32_16x16x32_bf16 v[112:115], v[48:51], v[92:95], v[112:115]
	v_mfma_f32_16x16x32_bf16 v[116:119], v[44:47], v[96:99], v[116:119]
	v_mfma_f32_16x16x32_bf16 v[120:123], v[48:51], v[96:99], v[120:123]
	s_waitcnt lgkmcnt(0)
	v_mfma_f32_16x16x32_bf16 v[108:111], v[52:55], v[100:103], v[108:111]
	v_mfma_f32_16x16x32_bf16 v[112:115], v[56:59], v[100:103], v[112:115]
	v_mfma_f32_16x16x32_bf16 v[116:119], v[52:55], v[104:107], v[116:119]
	v_mfma_f32_16x16x32_bf16 v[120:123], v[56:59], v[104:107], v[120:123]
	s_nop 7
	s_nop 7
	v_cvt_pk_bf16_f32 v124, v108, v109
	v_cvt_pk_bf16_f32 v125, v110, v111
	v_cvt_pk_bf16_f32 v126, v112, v113
	v_cvt_pk_bf16_f32 v127, v114, v115
	v_cvt_pk_bf16_f32 v128, v116, v117
	v_cvt_pk_bf16_f32 v129, v118, v119
	v_cvt_pk_bf16_f32 v130, v120, v121
	v_cvt_pk_bf16_f32 v131, v122, v123
	global_store_dwordx2 v248, v[124:125], s[18:19]
	global_store_dwordx2 v248, v[126:127], s[18:19] offset:32
	global_store_dwordx2 v247, v[128:129], s[18:19]
	global_store_dwordx2 v247, v[130:131], s[18:19] offset:32
	s_add_u32 s18, s18, 0x20000
	s_addc_u32 s19, s19, 0
	s_add_i32 s33, s33, 1
	s_waitcnt vmcnt(13)
	s_waitcnt lgkmcnt(0)
	s_barrier
	s_add_i32 m0, s46, 0x14000
	s_nop 0
	global_load_lds_dwordx4 v255, s[8:9]
	s_add_i32 m0, s46, 0x14400
	s_nop 0
	global_load_lds_dwordx4 v254, s[8:9]
	s_add_i32 m0, s47, 0x14000
	s_nop 0
	global_load_lds_dwordx4 v253, s[10:11]
	s_add_i32 m0, s48, 0x14000
	s_nop 0
	global_load_lds_dwordx4 v252, s[12:13]
	s_add_i32 m0, s48, 0x14400
	s_nop 0
	global_load_lds_dwordx4 v251, s[12:13]
	s_cmp_lt_u32 s33, 29
	s_cselect_b32 s43, 0x10000, 0
	s_add_u32 s8, s8, s43
	s_addc_u32 s9, s9, 0
	s_cmp_lt_u32 s33, 29
	s_cselect_b32 s43, 0x2000, 0
	s_add_u32 s10, s10, s43
	s_addc_u32 s11, s11, 0
	s_cmp_lt_u32 s33, 29
	s_cselect_b32 s43, 0x4000, 0
	s_add_u32 s12, s12, s43
	s_addc_u32 s13, s13, 0
	ds_read_b128 v[60:63], v241 offset:0
	ds_read_b128 v[12:15], v223 offset:12544
	ds_read_b128 v[16:19], v223 offset:16640
	ds_read_b128 v[64:67], v241 offset:4096
	ds_read_b128 v[68:71], v240 offset:0
	ds_read_b128 v[20:23], v222 offset:12544
	ds_read_b128 v[24:27], v222 offset:16640
	ds_read_b128 v[72:75], v240 offset:4096
	ds_read_b128 v[76:79], v239 offset:0
	ds_read_b128 v[28:31], v221 offset:12544
	ds_read_b128 v[32:35], v221 offset:16640
	ds_read_b128 v[80:83], v239 offset:4096
	s_waitcnt lgkmcnt(8)
	v_mfma_f32_16x16x32_bf16 v[108:111], v[12:15], v[60:63], 0
	v_mfma_f32_16x16x32_bf16 v[112:115], v[16:19], v[60:63], 0
	v_mfma_f32_16x16x32_bf16 v[116:119], v[12:15], v[64:67], 0
	v_mfma_f32_16x16x32_bf16 v[120:123], v[16:19], v[64:67], 0
	ds_read_b128 v[84:87], v238 offset:0
	ds_read_b128 v[36:39], v220 offset:12544
	ds_read_b128 v[40:43], v220 offset:16640
	ds_read_b128 v[88:91], v238 offset:4096
	s_waitcnt lgkmcnt(8)
	v_mfma_f32_16x16x32_bf16 v[108:111], v[20:23], v[68:71], v[108:111]
	v_mfma_f32_16x16x32_bf16 v[112:115], v[24:27], v[68:71], v[112:115]
	v_mfma_f32_16x16x32_bf16 v[116:119], v[20:23], v[72:75], v[116:119]
	v_mfma_f32_16x16x32_bf16 v[120:123], v[24:27], v[72:75], v[120:123]
	ds_read_b128 v[92:95], v231 offset:0
	ds_read_b128 v[44:47], v219 offset:12288
	ds_read_b128 v[48:51], v219 offset:14336
	ds_read_b128 v[96:99], v231 offset:2048
	s_waitcnt lgkmcnt(8)
	v_mfma_f32_16x16x32_bf16 v[108:111], v[28:31], v[76:79], v[108:111]
	v_mfma_f32_16x16x32_bf16 v[112:115], v[32:35], v[76:79], v[112:115]
	v_mfma_f32_16x16x32_bf16 v[116:119], v[28:31], v[80:83], v[116:119]
	v_mfma_f32_16x16x32_bf16 v[120:123], v[32:35], v[80:83], v[120:123]
	ds_read_b128 v[100:103], v230 offset:0
	ds_read_b128 v[52:55], v218 offset:12288
	ds_read_b128 v[56:59], v218 offset:14336
	ds_read_b128 v[104:107], v230 offset:2048
	s_waitcnt lgkmcnt(8)
	v_mfma_f32_16x16x32_bf16 v[108:111], v[36:39], v[84:87], v[108:111]
	v_mfma_f32_16x16x32_bf16 v[112:115], v[40:43], v[84:87], v[112:115]
	v_mfma_f32_16x16x32_bf16 v[116:119], v[36:39], v[88:91], v[116:119]
	v_mfma_f32_16x16x32_bf16 v[120:123], v[40:43], v[88:91], v[120:123]
	s_waitcnt lgkmcnt(4)
	v_mfma_f32_16x16x32_bf16 v[108:111], v[44:47], v[92:95], v[108:111]
	v_mfma_f32_16x16x32_bf16 v[112:115], v[48:51], v[92:95], v[112:115]
	v_mfma_f32_16x16x32_bf16 v[116:119], v[44:47], v[96:99], v[116:119]
	v_mfma_f32_16x16x32_bf16 v[120:123], v[48:51], v[96:99], v[120:123]
	s_waitcnt lgkmcnt(0)
	v_mfma_f32_16x16x32_bf16 v[108:111], v[52:55], v[100:103], v[108:111]
	v_mfma_f32_16x16x32_bf16 v[112:115], v[56:59], v[100:103], v[112:115]
	v_mfma_f32_16x16x32_bf16 v[116:119], v[52:55], v[104:107], v[116:119]
	v_mfma_f32_16x16x32_bf16 v[120:123], v[56:59], v[104:107], v[120:123]
	s_nop 7
	s_nop 7
	v_cvt_pk_bf16_f32 v124, v108, v109
	v_cvt_pk_bf16_f32 v125, v110, v111
	v_cvt_pk_bf16_f32 v126, v112, v113
	v_cvt_pk_bf16_f32 v127, v114, v115
	v_cvt_pk_bf16_f32 v128, v116, v117
	v_cvt_pk_bf16_f32 v129, v118, v119
	v_cvt_pk_bf16_f32 v130, v120, v121
	v_cvt_pk_bf16_f32 v131, v122, v123
	global_store_dwordx2 v248, v[124:125], s[18:19]
	global_store_dwordx2 v248, v[126:127], s[18:19] offset:32
	global_store_dwordx2 v247, v[128:129], s[18:19]
	global_store_dwordx2 v247, v[130:131], s[18:19] offset:32
	s_add_u32 s18, s18, 0x20000
	s_addc_u32 s19, s19, 0
	s_add_i32 s33, s33, 1
	s_waitcnt vmcnt(13)
	s_waitcnt lgkmcnt(0)
	s_barrier
	s_mov_b32 m0, s46
	s_nop 0
	global_load_lds_dwordx4 v255, s[8:9]
	s_add_i32 m0, s46, 0x400
	s_nop 0
	global_load_lds_dwordx4 v254, s[8:9]
	s_mov_b32 m0, s47
	s_nop 0
	global_load_lds_dwordx4 v253, s[10:11]
	s_mov_b32 m0, s48
	s_nop 0
	global_load_lds_dwordx4 v252, s[12:13]
	s_add_i32 m0, s48, 0x400
	s_nop 0
	global_load_lds_dwordx4 v251, s[12:13]
	s_cmp_lt_u32 s33, 29
	s_cselect_b32 s43, 0x10000, 0
	s_add_u32 s8, s8, s43
	s_addc_u32 s9, s9, 0
	s_cmp_lt_u32 s33, 29
	s_cselect_b32 s43, 0x2000, 0
	s_add_u32 s10, s10, s43
	s_addc_u32 s11, s11, 0
	s_cmp_lt_u32 s33, 29
	s_cselect_b32 s43, 0x4000, 0
	s_add_u32 s12, s12, s43
	s_addc_u32 s13, s13, 0
	ds_read_b128 v[60:63], v241 offset:40960
	ds_read_b128 v[12:15], v223 offset:0
	ds_read_b128 v[16:19], v223 offset:4096
	ds_read_b128 v[64:67], v241 offset:45056
	ds_read_b128 v[68:71], v240 offset:40960
	ds_read_b128 v[20:23], v222 offset:0
	ds_read_b128 v[24:27], v222 offset:4096
	ds_read_b128 v[72:75], v240 offset:45056
	ds_read_b128 v[76:79], v239 offset:40960
	ds_read_b128 v[28:31], v221 offset:0
	ds_read_b128 v[32:35], v221 offset:4096
	ds_read_b128 v[80:83], v239 offset:45056
	s_waitcnt lgkmcnt(8)
	v_mfma_f32_16x16x32_bf16 v[108:111], v[12:15], v[60:63], 0
	v_mfma_f32_16x16x32_bf16 v[112:115], v[16:19], v[60:63], 0
	v_mfma_f32_16x16x32_bf16 v[116:119], v[12:15], v[64:67], 0
	v_mfma_f32_16x16x32_bf16 v[120:123], v[16:19], v[64:67], 0
	ds_read_b128 v[84:87], v238 offset:40960
	ds_read_b128 v[36:39], v220 offset:0
	ds_read_b128 v[40:43], v220 offset:4096
	ds_read_b128 v[88:91], v238 offset:45056
	s_waitcnt lgkmcnt(8)
	v_mfma_f32_16x16x32_bf16 v[108:111], v[20:23], v[68:71], v[108:111]
	v_mfma_f32_16x16x32_bf16 v[112:115], v[24:27], v[68:71], v[112:115]
	v_mfma_f32_16x16x32_bf16 v[116:119], v[20:23], v[72:75], v[116:119]
	v_mfma_f32_16x16x32_bf16 v[120:123], v[24:27], v[72:75], v[120:123]
	ds_read_b128 v[92:95], v231 offset:40960
	ds_read_b128 v[44:47], v219 offset:0
	ds_read_b128 v[48:51], v219 offset:2048
	ds_read_b128 v[96:99], v231 offset:43008
	s_waitcnt lgkmcnt(8)
	v_mfma_f32_16x16x32_bf16 v[108:111], v[28:31], v[76:79], v[108:111]
	v_mfma_f32_16x16x32_bf16 v[112:115], v[32:35], v[76:79], v[112:115]
	v_mfma_f32_16x16x32_bf16 v[116:119], v[28:31], v[80:83], v[116:119]
	v_mfma_f32_16x16x32_bf16 v[120:123], v[32:35], v[80:83], v[120:123]
	ds_read_b128 v[100:103], v230 offset:40960
	ds_read_b128 v[52:55], v218 offset:0
	ds_read_b128 v[56:59], v218 offset:2048
	ds_read_b128 v[104:107], v230 offset:43008
	s_waitcnt lgkmcnt(8)
	v_mfma_f32_16x16x32_bf16 v[108:111], v[36:39], v[84:87], v[108:111]
	v_mfma_f32_16x16x32_bf16 v[112:115], v[40:43], v[84:87], v[112:115]
	v_mfma_f32_16x16x32_bf16 v[116:119], v[36:39], v[88:91], v[116:119]
	v_mfma_f32_16x16x32_bf16 v[120:123], v[40:43], v[88:91], v[120:123]
	s_waitcnt lgkmcnt(4)
	v_mfma_f32_16x16x32_bf16 v[108:111], v[44:47], v[92:95], v[108:111]
	v_mfma_f32_16x16x32_bf16 v[112:115], v[48:51], v[92:95], v[112:115]
	v_mfma_f32_16x16x32_bf16 v[116:119], v[44:47], v[96:99], v[116:119]
	v_mfma_f32_16x16x32_bf16 v[120:123], v[48:51], v[96:99], v[120:123]
	s_waitcnt lgkmcnt(0)
	v_mfma_f32_16x16x32_bf16 v[108:111], v[52:55], v[100:103], v[108:111]
	v_mfma_f32_16x16x32_bf16 v[112:115], v[56:59], v[100:103], v[112:115]
	v_mfma_f32_16x16x32_bf16 v[116:119], v[52:55], v[104:107], v[116:119]
	v_mfma_f32_16x16x32_bf16 v[120:123], v[56:59], v[104:107], v[120:123]
	s_nop 7
	s_nop 7
	v_cvt_pk_bf16_f32 v124, v108, v109
	v_cvt_pk_bf16_f32 v125, v110, v111
	v_cvt_pk_bf16_f32 v126, v112, v113
	v_cvt_pk_bf16_f32 v127, v114, v115
	v_cvt_pk_bf16_f32 v128, v116, v117
	v_cvt_pk_bf16_f32 v129, v118, v119
	v_cvt_pk_bf16_f32 v130, v120, v121
	v_cvt_pk_bf16_f32 v131, v122, v123
	global_store_dwordx2 v248, v[124:125], s[18:19]
	global_store_dwordx2 v248, v[126:127], s[18:19] offset:32
	global_store_dwordx2 v247, v[128:129], s[18:19]
	global_store_dwordx2 v247, v[130:131], s[18:19] offset:32
	s_add_u32 s18, s18, 0x20000
	s_addc_u32 s19, s19, 0
	s_add_i32 s33, s33, 1
	s_waitcnt vmcnt(13)
	s_waitcnt lgkmcnt(0)
	s_barrier
	s_add_i32 m0, s46, 0xa000
	s_nop 0
	global_load_lds_dwordx4 v255, s[8:9]
	s_add_i32 m0, s46, 0xa400
	s_nop 0
	global_load_lds_dwordx4 v254, s[8:9]
	s_add_i32 m0, s47, 0xa000
	s_nop 0
	global_load_lds_dwordx4 v253, s[10:11]
	s_add_i32 m0, s48, 0xa000
	s_nop 0
	global_load_lds_dwordx4 v252, s[12:13]
	s_add_i32 m0, s48, 0xa400
	s_nop 0
	global_load_lds_dwordx4 v251, s[12:13]
	s_cmp_lt_u32 s33, 29
	s_cselect_b32 s43, 0x10000, 0
	s_add_u32 s8, s8, s43
	s_addc_u32 s9, s9, 0
	s_cmp_lt_u32 s33, 29
	s_cselect_b32 s43, 0x2000, 0
	s_add_u32 s10, s10, s43
	s_addc_u32 s11, s11, 0
	s_cmp_lt_u32 s33, 29
	s_cselect_b32 s43, 0x4000, 0
	s_add_u32 s12, s12, s43
	s_addc_u32 s13, s13, 0
	ds_read_b128 v[60:63], v235 offset:0
	ds_read_b128 v[12:15], v223 offset:12544
	ds_read_b128 v[16:19], v223 offset:16640
	ds_read_b128 v[64:67], v235 offset:4096
	ds_read_b128 v[68:71], v234 offset:0
	ds_read_b128 v[20:23], v222 offset:12544
	ds_read_b128 v[24:27], v222 offset:16640
	ds_read_b128 v[72:75], v234 offset:4096
	ds_read_b128 v[76:79], v233 offset:0
	ds_read_b128 v[28:31], v221 offset:12544
	ds_read_b128 v[32:35], v221 offset:16640
	ds_read_b128 v[80:83], v233 offset:4096
	s_waitcnt lgkmcnt(8)
	v_mfma_f32_16x16x32_bf16 v[108:111], v[12:15], v[60:63], 0
	v_mfma_f32_16x16x32_bf16 v[112:115], v[16:19], v[60:63], 0
	v_mfma_f32_16x16x32_bf16 v[116:119], v[12:15], v[64:67], 0
	v_mfma_f32_16x16x32_bf16 v[120:123], v[16:19], v[64:67], 0
	ds_read_b128 v[84:87], v232 offset:0
	ds_read_b128 v[36:39], v220 offset:12544
	ds_read_b128 v[40:43], v220 offset:16640
	ds_read_b128 v[88:91], v232 offset:4096
	s_waitcnt lgkmcnt(8)
	v_mfma_f32_16x16x32_bf16 v[108:111], v[20:23], v[68:71], v[108:111]
	v_mfma_f32_16x16x32_bf16 v[112:115], v[24:27], v[68:71], v[112:115]
	v_mfma_f32_16x16x32_bf16 v[116:119], v[20:23], v[72:75], v[116:119]
	v_mfma_f32_16x16x32_bf16 v[120:123], v[24:27], v[72:75], v[120:123]
	ds_read_b128 v[92:95], v229 offset:0
	ds_read_b128 v[44:47], v219 offset:12288
	ds_read_b128 v[48:51], v219 offset:14336
	ds_read_b128 v[96:99], v229 offset:2048
	s_waitcnt lgkmcnt(8)
	v_mfma_f32_16x16x32_bf16 v[108:111], v[28:31], v[76:79], v[108:111]
	v_mfma_f32_16x16x32_bf16 v[112:115], v[32:35], v[76:79], v[112:115]
	v_mfma_f32_16x16x32_bf16 v[116:119], v[28:31], v[80:83], v[116:119]
	v_mfma_f32_16x16x32_bf16 v[120:123], v[32:35], v[80:83], v[120:123]
	ds_read_b128 v[100:103], v228 offset:0
	ds_read_b128 v[52:55], v218 offset:12288
	ds_read_b128 v[56:59], v218 offset:14336
	ds_read_b128 v[104:107], v228 offset:2048
	s_waitcnt lgkmcnt(8)
	v_mfma_f32_16x16x32_bf16 v[108:111], v[36:39], v[84:87], v[108:111]
	v_mfma_f32_16x16x32_bf16 v[112:115], v[40:43], v[84:87], v[112:115]
	v_mfma_f32_16x16x32_bf16 v[116:119], v[36:39], v[88:91], v[116:119]
	v_mfma_f32_16x16x32_bf16 v[120:123], v[40:43], v[88:91], v[120:123]
	s_waitcnt lgkmcnt(4)
	v_mfma_f32_16x16x32_bf16 v[108:111], v[44:47], v[92:95], v[108:111]
	v_mfma_f32_16x16x32_bf16 v[112:115], v[48:51], v[92:95], v[112:115]
	v_mfma_f32_16x16x32_bf16 v[116:119], v[44:47], v[96:99], v[116:119]
	v_mfma_f32_16x16x32_bf16 v[120:123], v[48:51], v[96:99], v[120:123]
	s_waitcnt lgkmcnt(0)
	v_mfma_f32_16x16x32_bf16 v[108:111], v[52:55], v[100:103], v[108:111]
	v_mfma_f32_16x16x32_bf16 v[112:115], v[56:59], v[100:103], v[112:115]
	v_mfma_f32_16x16x32_bf16 v[116:119], v[52:55], v[104:107], v[116:119]
	v_mfma_f32_16x16x32_bf16 v[120:123], v[56:59], v[104:107], v[120:123]
	s_nop 7
	s_nop 7
	v_cvt_pk_bf16_f32 v124, v108, v109
	v_cvt_pk_bf16_f32 v125, v110, v111
	v_cvt_pk_bf16_f32 v126, v112, v113
	v_cvt_pk_bf16_f32 v127, v114, v115
	v_cvt_pk_bf16_f32 v128, v116, v117
	v_cvt_pk_bf16_f32 v129, v118, v119
	v_cvt_pk_bf16_f32 v130, v120, v121
	v_cvt_pk_bf16_f32 v131, v122, v123
	global_store_dwordx2 v248, v[124:125], s[18:19]
	global_store_dwordx2 v248, v[126:127], s[18:19] offset:32
	global_store_dwordx2 v247, v[128:129], s[18:19]
	global_store_dwordx2 v247, v[130:131], s[18:19] offset:32
	s_add_u32 s18, s18, 0x20000
	s_addc_u32 s19, s19, 0
	s_add_i32 s33, s33, 1
	s_waitcnt vmcnt(13)
	s_waitcnt lgkmcnt(0)
	s_barrier
	s_cmp_lt_u32 s33, 30
	s_cbranch_scc1 .Lp3O_loop
	s_add_i32 m0, s46, 0x14000
	s_nop 0
	global_load_lds_dwordx4 v255, s[8:9]
	s_add_i32 m0, s46, 0x14400
	s_nop 0
	global_load_lds_dwordx4 v254, s[8:9]
	s_add_i32 m0, s47, 0x14000
	s_nop 0
	global_load_lds_dwordx4 v253, s[10:11]
	s_add_i32 m0, s48, 0x14000
	s_nop 0
	global_load_lds_dwordx4 v252, s[12:13]
	s_add_i32 m0, s48, 0x14400
	s_nop 0
	global_load_lds_dwordx4 v251, s[12:13]
	s_cmp_lt_u32 s33, 29
	s_cselect_b32 s43, 0x10000, 0
	s_add_u32 s8, s8, s43
	s_addc_u32 s9, s9, 0
	s_cmp_lt_u32 s33, 29
	s_cselect_b32 s43, 0x2000, 0
	s_add_u32 s10, s10, s43
	s_addc_u32 s11, s11, 0
	s_cmp_lt_u32 s33, 29
	s_cselect_b32 s43, 0x4000, 0
	s_add_u32 s12, s12, s43
	s_addc_u32 s13, s13, 0
	ds_read_b128 v[60:63], v241 offset:0
	ds_read_b128 v[12:15], v223 offset:0
	ds_read_b128 v[16:19], v223 offset:4096
	ds_read_b128 v[64:67], v241 offset:4096
	ds_read_b128 v[68:71], v240 offset:0
	ds_read_b128 v[20:23], v222 offset:0
	ds_read_b128 v[24:27], v222 offset:4096
	ds_read_b128 v[72:75], v240 offset:4096
	ds_read_b128 v[76:79], v239 offset:0
	ds_read_b128 v[28:31], v221 offset:0
	ds_read_b128 v[32:35], v221 offset:4096
	ds_read_b128 v[80:83], v239 offset:4096
	s_waitcnt lgkmcnt(8)
	v_mfma_f32_16x16x32_bf16 v[108:111], v[12:15], v[60:63], 0
	v_mfma_f32_16x16x32_bf16 v[112:115], v[16:19], v[60:63], 0
	v_mfma_f32_16x16x32_bf16 v[116:119], v[12:15], v[64:67], 0
	v_mfma_f32_16x16x32_bf16 v[120:123], v[16:19], v[64:67], 0
	ds_read_b128 v[84:87], v238 offset:0
	ds_read_b128 v[36:39], v220 offset:0
	ds_read_b128 v[40:43], v220 offset:4096
	ds_read_b128 v[88:91], v238 offset:4096
	s_waitcnt lgkmcnt(8)
	v_mfma_f32_16x16x32_bf16 v[108:111], v[20:23], v[68:71], v[108:111]
	v_mfma_f32_16x16x32_bf16 v[112:115], v[24:27], v[68:71], v[112:115]
	v_mfma_f32_16x16x32_bf16 v[116:119], v[20:23], v[72:75], v[116:119]
	v_mfma_f32_16x16x32_bf16 v[120:123], v[24:27], v[72:75], v[120:123]
	ds_read_b128 v[92:95], v231 offset:0
	ds_read_b128 v[44:47], v219 offset:0
	ds_read_b128 v[48:51], v219 offset:2048
	ds_read_b128 v[96:99], v231 offset:2048
	s_waitcnt lgkmcnt(8)
	v_mfma_f32_16x16x32_bf16 v[108:111], v[28:31], v[76:79], v[108:111]
	v_mfma_f32_16x16x32_bf16 v[112:115], v[32:35], v[76:79], v[112:115]
	v_mfma_f32_16x16x32_bf16 v[116:119], v[28:31], v[80:83], v[116:119]
	v_mfma_f32_16x16x32_bf16 v[120:123], v[32:35], v[80:83], v[120:123]
	ds_read_b128 v[100:103], v230 offset:0
	ds_read_b128 v[52:55], v218 offset:0
	ds_read_b128 v[56:59], v218 offset:2048
	ds_read_b128 v[104:107], v230 offset:2048
	s_waitcnt lgkmcnt(8)
	v_mfma_f32_16x16x32_bf16 v[108:111], v[36:39], v[84:87], v[108:111]
	v_mfma_f32_16x16x32_bf16 v[112:115], v[40:43], v[84:87], v[112:115]
	v_mfma_f32_16x16x32_bf16 v[116:119], v[36:39], v[88:91], v[116:119]
	v_mfma_f32_16x16x32_bf16 v[120:123], v[40:43], v[88:91], v[120:123]
	s_waitcnt lgkmcnt(4)
	v_mfma_f32_16x16x32_bf16 v[108:111], v[44:47], v[92:95], v[108:111]
	v_mfma_f32_16x16x32_bf16 v[112:115], v[48:51], v[92:95], v[112:115]
	v_mfma_f32_16x16x32_bf16 v[116:119], v[44:47], v[96:99], v[116:119]
	v_mfma_f32_16x16x32_bf16 v[120:123], v[48:51], v[96:99], v[120:123]
	s_waitcnt lgkmcnt(0)
	v_mfma_f32_16x16x32_bf16 v[108:111], v[52:55], v[100:103], v[108:111]
	v_mfma_f32_16x16x32_bf16 v[112:115], v[56:59], v[100:103], v[112:115]
	v_mfma_f32_16x16x32_bf16 v[116:119], v[52:55], v[104:107], v[116:119]
	v_mfma_f32_16x16x32_bf16 v[120:123], v[56:59], v[104:107], v[120:123]
	s_nop 7
	s_nop 7
	v_cvt_pk_bf16_f32 v124, v108, v109
	v_cvt_pk_bf16_f32 v125, v110, v111
	v_cvt_pk_bf16_f32 v126, v112, v113
	v_cvt_pk_bf16_f32 v127, v114, v115
	v_cvt_pk_bf16_f32 v128, v116, v117
	v_cvt_pk_bf16_f32 v129, v118, v119
	v_cvt_pk_bf16_f32 v130, v120, v121
	v_cvt_pk_bf16_f32 v131, v122, v123
	global_store_dwordx2 v248, v[124:125], s[18:19]
	global_store_dwordx2 v248, v[126:127], s[18:19] offset:32
	global_store_dwordx2 v247, v[128:129], s[18:19]
	global_store_dwordx2 v247, v[130:131], s[18:19] offset:32
	s_add_u32 s18, s18, 0x20000
	s_addc_u32 s19, s19, 0
	s_add_i32 s33, s33, 1
	s_waitcnt vmcnt(13)
	s_waitcnt lgkmcnt(0)
	s_barrier
; #define LAS __attribute__((address_space(3)))
; __device__ __forceinline__ void gla_scan_item(const Ctx& C, int item, LAS unsigned char* lds, int tid) {
;     const int jx = item >> 3, bh = (item & 7) * 4 + (jx >> 3), sl = jx & 7, b = bh >> 2, h = bh & 3;
	s_mov_b32 m0, s46
	s_nop 0
	global_load_lds_dwordx4 v255, s[8:9]
	s_add_i32 m0, s46, 0x400
	s_nop 0
	global_load_lds_dwordx4 v254, s[8:9]
	s_mov_b32 m0, s47
	s_nop 0
	global_load_lds_dwordx4 v253, s[10:11]
	s_mov_b32 m0, s48
	s_nop 0
	global_load_lds_dwordx4 v252, s[12:13]
	s_add_i32 m0, s48, 0x400
	s_nop 0
	global_load_lds_dwordx4 v251, s[12:13]
	s_cmp_lt_u32 s33, 29
	s_cselect_b32 s43, 0x10000, 0
	s_add_u32 s8, s8, s43
	s_addc_u32 s9, s9, 0
	s_cmp_lt_u32 s33, 29
	s_cselect_b32 s43, 0x2000, 0
	s_add_u32 s10, s10, s43
	s_addc_u32 s11, s11, 0
	s_cmp_lt_u32 s33, 29
	s_cselect_b32 s43, 0x4000, 0
	s_add_u32 s12, s12, s43
	s_addc_u32 s13, s13, 0
	ds_read_b128 v[60:63], v241 offset:40960
	ds_read_b128 v[12:15], v223 offset:12544
	ds_read_b128 v[16:19], v223 offset:16640
	ds_read_b128 v[64:67], v241 offset:45056
	ds_read_b128 v[68:71], v240 offset:40960
	ds_read_b128 v[20:23], v222 offset:12544
	ds_read_b128 v[24:27], v222 offset:16640
	ds_read_b128 v[72:75], v240 offset:45056
	ds_read_b128 v[76:79], v239 offset:40960
	ds_read_b128 v[28:31], v221 offset:12544
	ds_read_b128 v[32:35], v221 offset:16640
	ds_read_b128 v[80:83], v239 offset:45056
	s_waitcnt lgkmcnt(8)
	v_mfma_f32_16x16x32_bf16 v[108:111], v[12:15], v[60:63], 0
	v_mfma_f32_16x16x32_bf16 v[112:115], v[16:19], v[60:63], 0
	v_mfma_f32_16x16x32_bf16 v[116:119], v[12:15], v[64:67], 0
	v_mfma_f32_16x16x32_bf16 v[120:123], v[16:19], v[64:67], 0
	ds_read_b128 v[84:87], v238 offset:40960
	ds_read_b128 v[36:39], v220 offset:12544
	ds_read_b128 v[40:43], v220 offset:16640
	ds_read_b128 v[88:91], v238 offset:45056
	s_waitcnt lgkmcnt(8)
	v_mfma_f32_16x16x32_bf16 v[108:111], v[20:23], v[68:71], v[108:111]
	v_mfma_f32_16x16x32_bf16 v[112:115], v[24:27], v[68:71], v[112:115]
	v_mfma_f32_16x16x32_bf16 v[116:119], v[20:23], v[72:75], v[116:119]
	v_mfma_f32_16x16x32_bf16 v[120:123], v[24:27], v[72:75], v[120:123]
	ds_read_b128 v[92:95], v231 offset:40960
	ds_read_b128 v[44:47], v219 offset:12288
	ds_read_b128 v[48:51], v219 offset:14336
	ds_read_b128 v[96:99], v231 offset:43008
	s_waitcnt lgkmcnt(8)
	v_mfma_f32_16x16x32_bf16 v[108:111], v[28:31], v[76:79], v[108:111]
	v_mfma_f32_16x16x32_bf16 v[112:115], v[32:35], v[76:79], v[112:115]
	v_mfma_f32_16x16x32_bf16 v[116:119], v[28:31], v[80:83], v[116:119]
	v_mfma_f32_16x16x32_bf16 v[120:123], v[32:35], v[80:83], v[120:123]
	ds_read_b128 v[100:103], v230 offset:40960
	ds_read_b128 v[52:55], v218 offset:12288
	ds_read_b128 v[56:59], v218 offset:14336
	ds_read_b128 v[104:107], v230 offset:43008
	s_waitcnt lgkmcnt(8)
	v_mfma_f32_16x16x32_bf16 v[108:111], v[36:39], v[84:87], v[108:111]
	v_mfma_f32_16x16x32_bf16 v[112:115], v[40:43], v[84:87], v[112:115]
	v_mfma_f32_16x16x32_bf16 v[116:119], v[36:39], v[88:91], v[116:119]
	v_mfma_f32_16x16x32_bf16 v[120:123], v[40:43], v[88:91], v[120:123]
	s_waitcnt lgkmcnt(4)
	v_mfma_f32_16x16x32_bf16 v[108:111], v[44:47], v[92:95], v[108:111]
	v_mfma_f32_16x16x32_bf16 v[112:115], v[48:51], v[92:95], v[112:115]
	v_mfma_f32_16x16x32_bf16 v[116:119], v[44:47], v[96:99], v[116:119]
	v_mfma_f32_16x16x32_bf16 v[120:123], v[48:51], v[96:99], v[120:123]
	s_waitcnt lgkmcnt(0)
	v_mfma_f32_16x16x32_bf16 v[108:111], v[52:55], v[100:103], v[108:111]
	v_mfma_f32_16x16x32_bf16 v[112:115], v[56:59], v[100:103], v[112:115]
	v_mfma_f32_16x16x32_bf16 v[116:119], v[52:55], v[104:107], v[116:119]
	v_mfma_f32_16x16x32_bf16 v[120:123], v[56:59], v[104:107], v[120:123]
	s_nop 7
	s_nop 7
	v_cvt_pk_bf16_f32 v124, v108, v109
	v_cvt_pk_bf16_f32 v125, v110, v111
	v_cvt_pk_bf16_f32 v126, v112, v113
	v_cvt_pk_bf16_f32 v127, v114, v115
	v_cvt_pk_bf16_f32 v128, v116, v117
	v_cvt_pk_bf16_f32 v129, v118, v119
	v_cvt_pk_bf16_f32 v130, v120, v121
	v_cvt_pk_bf16_f32 v131, v122, v123
	global_store_dwordx2 v248, v[124:125], s[18:19]
	global_store_dwordx2 v248, v[126:127], s[18:19] offset:32
	global_store_dwordx2 v247, v[128:129], s[18:19]
	global_store_dwordx2 v247, v[130:131], s[18:19] offset:32
	s_add_u32 s18, s18, 0x20000
	s_addc_u32 s19, s19, 0
	s_add_i32 s33, s33, 1
	s_waitcnt vmcnt(13)
	s_waitcnt lgkmcnt(0)
	s_barrier
	s_waitcnt vmcnt(0) lgkmcnt(0)
	s_barrier
	s_add_i32 s3, s3, s42
	s_cmpk_lt_i32 s3, 0x100
	s_cbranch_scc1 .Lp3O_item
	s_branch .Lp3_done

.Lp3S_loop:
	s_add_i32 m0, s46, 0x14000
	s_nop 0
	global_load_lds_dwordx4 v255, s[8:9]
	s_add_i32 m0, s46, 0x14400
	s_nop 0
	global_load_lds_dwordx4 v254, s[8:9]
	s_add_i32 m0, s47, 0x14000
	s_nop 0
	global_load_lds_dwordx4 v253, s[10:11]
	s_add_i32 m0, s48, 0x14000
	s_nop 0
	global_load_lds_dwordx4 v252, s[12:13]
	s_add_i32 m0, s48, 0x14400
	s_nop 0
	global_load_lds_dwordx4 v251, s[12:13]
	s_cmp_lt_u32 s33, 29
	s_cselect_b32 s43, 0x10000, 0
	s_add_u32 s8, s8, s43
	s_addc_u32 s9, s9, 0
	s_cmp_lt_u32 s33, 29
	s_cselect_b32 s43, 0x2000, 0
	s_add_u32 s10, s10, s43
	s_addc_u32 s11, s11, 0
	s_cmp_lt_u32 s33, 29
	s_cselect_b32 s43, 0x4000, 0
	s_add_u32 s12, s12, s43
	s_addc_u32 s13, s13, 0
	ds_read_b128 v[44:47], v217 offset:0
	ds_read_b128 v[48:51], v217 offset:2048
	ds_read_b128 v[12:15], v227 offset:0
	ds_read_b128 v[16:19], v227 offset:2048
	ds_read_b128 v[20:23], v227 offset:4096
	ds_read_b128 v[24:27], v227 offset:6144
	ds_read_b128 v[52:55], v216 offset:0
	ds_read_b128 v[56:59], v216 offset:2048
	ds_read_b128 v[28:31], v226 offset:0
	ds_read_b128 v[32:35], v226 offset:2048
	ds_read_b128 v[36:39], v226 offset:4096
	ds_read_b128 v[40:43], v226 offset:6144
	s_waitcnt vmcnt(23)
	v_pk_mul_f32 v[60:61], v[60:61], v[92:93]
	v_pk_mul_f32 v[62:63], v[62:63], v[94:95]
	v_pk_mul_f32 v[64:65], v[64:65], v[92:93]
	v_pk_mul_f32 v[66:67], v[66:67], v[94:95]
	v_pk_mul_f32 v[68:69], v[68:69], v[96:97]
	v_pk_mul_f32 v[70:71], v[70:71], v[98:99]
	v_pk_mul_f32 v[72:73], v[72:73], v[96:97]
	v_pk_mul_f32 v[74:75], v[74:75], v[98:99]
	v_pk_mul_f32 v[76:77], v[76:77], v[100:101]
	v_pk_mul_f32 v[78:79], v[78:79], v[102:103]
	v_pk_mul_f32 v[80:81], v[80:81], v[100:101]
	v_pk_mul_f32 v[82:83], v[82:83], v[102:103]
	v_pk_mul_f32 v[84:85], v[84:85], v[104:105]
	v_pk_mul_f32 v[86:87], v[86:87], v[106:107]
	v_pk_mul_f32 v[88:89], v[88:89], v[104:105]
	v_pk_mul_f32 v[90:91], v[90:91], v[106:107]
	s_waitcnt lgkmcnt(6)
	v_mfma_f32_16x16x32_bf16 v[60:63], v[12:15], v[44:47], v[60:63]
	v_mfma_f32_16x16x32_bf16 v[64:67], v[12:15], v[48:51], v[64:67]
	v_mfma_f32_16x16x32_bf16 v[68:71], v[16:19], v[44:47], v[68:71]
	v_mfma_f32_16x16x32_bf16 v[72:75], v[16:19], v[48:51], v[72:75]
	v_mfma_f32_16x16x32_bf16 v[76:79], v[20:23], v[44:47], v[76:79]
	v_mfma_f32_16x16x32_bf16 v[80:83], v[20:23], v[48:51], v[80:83]
	v_mfma_f32_16x16x32_bf16 v[84:87], v[24:27], v[44:47], v[84:87]
	v_mfma_f32_16x16x32_bf16 v[88:91], v[24:27], v[48:51], v[88:91]
	s_waitcnt lgkmcnt(0)
	v_mfma_f32_16x16x32_bf16 v[60:63], v[28:31], v[52:55], v[60:63]
	v_mfma_f32_16x16x32_bf16 v[64:67], v[28:31], v[56:59], v[64:67]
	v_mfma_f32_16x16x32_bf16 v[68:71], v[32:35], v[52:55], v[68:71]
	v_mfma_f32_16x16x32_bf16 v[72:75], v[32:35], v[56:59], v[72:75]
	v_mfma_f32_16x16x32_bf16 v[76:79], v[36:39], v[52:55], v[76:79]
	v_mfma_f32_16x16x32_bf16 v[80:83], v[36:39], v[56:59], v[80:83]
	v_mfma_f32_16x16x32_bf16 v[84:87], v[40:43], v[52:55], v[84:87]
	v_mfma_f32_16x16x32_bf16 v[88:91], v[40:43], v[56:59], v[88:91]
	s_nop 3
	global_load_dwordx4 v[92:95], v249, s[16:17] offset:0
	global_load_dwordx4 v[96:99], v249, s[16:17] offset:64
	global_load_dwordx4 v[100:103], v249, s[16:17] offset:128
	global_load_dwordx4 v[104:107], v249, s[16:17] offset:192
	s_cmp_lt_u32 s33, 28
	s_cselect_b32 s43, 0x200, 0
	s_add_u32 s16, s16, s43
	s_addc_u32 s17, s17, 0
	s_add_i32 s33, s33, 1
	s_nop 7
	s_nop 7
	v_cvt_pk_bf16_f32 v140, v60, v61
	v_cvt_pk_bf16_f32 v141, v62, v63
	ds_write_b64 v215, v[140:141] offset:12544
	v_cvt_pk_bf16_f32 v144, v64, v65
	v_cvt_pk_bf16_f32 v145, v66, v67
	ds_write_b64 v215, v[144:145] offset:16640
	s_nop 1
	v_cvt_pk_bf16_f32 v140, v68, v69
	v_cvt_pk_bf16_f32 v141, v70, v71
	ds_write_b64 v214, v[140:141] offset:12544
	v_cvt_pk_bf16_f32 v144, v72, v73
	v_cvt_pk_bf16_f32 v145, v74, v75
	ds_write_b64 v214, v[144:145] offset:16640
	s_nop 1
	v_cvt_pk_bf16_f32 v140, v76, v77
	v_cvt_pk_bf16_f32 v141, v78, v79
	ds_write_b64 v213, v[140:141] offset:12544
	v_cvt_pk_bf16_f32 v144, v80, v81
	v_cvt_pk_bf16_f32 v145, v82, v83
	ds_write_b64 v213, v[144:145] offset:16640
	s_nop 1
	v_cvt_pk_bf16_f32 v140, v84, v85
	v_cvt_pk_bf16_f32 v141, v86, v87
	ds_write_b64 v212, v[140:141] offset:12544
	v_cvt_pk_bf16_f32 v144, v88, v89
	v_cvt_pk_bf16_f32 v145, v90, v91
	ds_write_b64 v212, v[144:145] offset:16640
	s_nop 1
	s_waitcnt vmcnt(13)
	s_waitcnt lgkmcnt(0)
	s_barrier
	s_mov_b32 m0, s46
	s_nop 0
	global_load_lds_dwordx4 v255, s[8:9]
	s_add_i32 m0, s46, 0x400
	s_nop 0
	global_load_lds_dwordx4 v254, s[8:9]
	s_mov_b32 m0, s47
	s_nop 0
	global_load_lds_dwordx4 v253, s[10:11]
	s_mov_b32 m0, s48
	s_nop 0
	global_load_lds_dwordx4 v252, s[12:13]
	s_add_i32 m0, s48, 0x400
	s_nop 0
	global_load_lds_dwordx4 v251, s[12:13]
	s_cmp_lt_u32 s33, 29
	s_cselect_b32 s43, 0x10000, 0
	s_add_u32 s8, s8, s43
	s_addc_u32 s9, s9, 0
	s_cmp_lt_u32 s33, 29
	s_cselect_b32 s43, 0x2000, 0
	s_add_u32 s10, s10, s43
	s_addc_u32 s11, s11, 0
	s_cmp_lt_u32 s33, 29
	s_cselect_b32 s43, 0x4000, 0
	s_add_u32 s12, s12, s43
	s_addc_u32 s13, s13, 0
	ds_read_b128 v[44:47], v217 offset:12288
	ds_read_b128 v[48:51], v217 offset:14336
	ds_read_b128 v[12:15], v227 offset:40960
	ds_read_b128 v[16:19], v227 offset:43008
	ds_read_b128 v[20:23], v227 offset:45056
	ds_read_b128 v[24:27], v227 offset:47104
	ds_read_b128 v[52:55], v216 offset:12288
	ds_read_b128 v[56:59], v216 offset:14336
	ds_read_b128 v[28:31], v226 offset:40960
	ds_read_b128 v[32:35], v226 offset:43008
	ds_read_b128 v[36:39], v226 offset:45056
	ds_read_b128 v[40:43], v226 offset:47104
	s_waitcnt vmcnt(23)
	v_pk_mul_f32 v[60:61], v[60:61], v[108:109]
	v_pk_mul_f32 v[62:63], v[62:63], v[110:111]
	v_pk_mul_f32 v[64:65], v[64:65], v[108:109]
	v_pk_mul_f32 v[66:67], v[66:67], v[110:111]
	v_pk_mul_f32 v[68:69], v[68:69], v[112:113]
	v_pk_mul_f32 v[70:71], v[70:71], v[114:115]
	v_pk_mul_f32 v[72:73], v[72:73], v[112:113]
	v_pk_mul_f32 v[74:75], v[74:75], v[114:115]
	v_pk_mul_f32 v[76:77], v[76:77], v[116:117]
	v_pk_mul_f32 v[78:79], v[78:79], v[118:119]
	v_pk_mul_f32 v[80:81], v[80:81], v[116:117]
	v_pk_mul_f32 v[82:83], v[82:83], v[118:119]
	v_pk_mul_f32 v[84:85], v[84:85], v[120:121]
	v_pk_mul_f32 v[86:87], v[86:87], v[122:123]
	v_pk_mul_f32 v[88:89], v[88:89], v[120:121]
	v_pk_mul_f32 v[90:91], v[90:91], v[122:123]
	s_waitcnt lgkmcnt(6)
	v_mfma_f32_16x16x32_bf16 v[60:63], v[12:15], v[44:47], v[60:63]
	v_mfma_f32_16x16x32_bf16 v[64:67], v[12:15], v[48:51], v[64:67]
	v_mfma_f32_16x16x32_bf16 v[68:71], v[16:19], v[44:47], v[68:71]
	v_mfma_f32_16x16x32_bf16 v[72:75], v[16:19], v[48:51], v[72:75]
	v_mfma_f32_16x16x32_bf16 v[76:79], v[20:23], v[44:47], v[76:79]
	v_mfma_f32_16x16x32_bf16 v[80:83], v[20:23], v[48:51], v[80:83]
	v_mfma_f32_16x16x32_bf16 v[84:87], v[24:27], v[44:47], v[84:87]
	v_mfma_f32_16x16x32_bf16 v[88:91], v[24:27], v[48:51], v[88:91]
	s_waitcnt lgkmcnt(0)
	v_mfma_f32_16x16x32_bf16 v[60:63], v[28:31], v[52:55], v[60:63]
	v_mfma_f32_16x16x32_bf16 v[64:67], v[28:31], v[56:59], v[64:67]
	v_mfma_f32_16x16x32_bf16 v[68:71], v[32:35], v[52:55], v[68:71]
	v_mfma_f32_16x16x32_bf16 v[72:75], v[32:35], v[56:59], v[72:75]
	v_mfma_f32_16x16x32_bf16 v[76:79], v[36:39], v[52:55], v[76:79]
	v_mfma_f32_16x16x32_bf16 v[80:83], v[36:39], v[56:59], v[80:83]
	v_mfma_f32_16x16x32_bf16 v[84:87], v[40:43], v[52:55], v[84:87]
	v_mfma_f32_16x16x32_bf16 v[88:91], v[40:43], v[56:59], v[88:91]
	s_nop 3
	global_load_dwordx4 v[108:111], v249, s[16:17] offset:0
	global_load_dwordx4 v[112:115], v249, s[16:17] offset:64
	global_load_dwordx4 v[116:119], v249, s[16:17] offset:128
	global_load_dwordx4 v[120:123], v249, s[16:17] offset:192
	s_cmp_lt_u32 s33, 28
	s_cselect_b32 s43, 0x200, 0
	s_add_u32 s16, s16, s43
	s_addc_u32 s17, s17, 0
	s_add_i32 s33, s33, 1
	s_nop 7
	s_nop 7
	v_cvt_pk_bf16_f32 v140, v60, v61
	v_cvt_pk_bf16_f32 v141, v62, v63
	ds_write_b64 v215, v[140:141] offset:0
	v_cvt_pk_bf16_f32 v144, v64, v65
	v_cvt_pk_bf16_f32 v145, v66, v67
	ds_write_b64 v215, v[144:145] offset:4096
	s_nop 1
	v_cvt_pk_bf16_f32 v140, v68, v69
	v_cvt_pk_bf16_f32 v141, v70, v71
	ds_write_b64 v214, v[140:141] offset:0
	v_cvt_pk_bf16_f32 v144, v72, v73
	v_cvt_pk_bf16_f32 v145, v74, v75
	ds_write_b64 v214, v[144:145] offset:4096
	s_nop 1
	v_cvt_pk_bf16_f32 v140, v76, v77
	v_cvt_pk_bf16_f32 v141, v78, v79
	ds_write_b64 v213, v[140:141] offset:0
	v_cvt_pk_bf16_f32 v144, v80, v81
	v_cvt_pk_bf16_f32 v145, v82, v83
	ds_write_b64 v213, v[144:145] offset:4096
	s_nop 1
	v_cvt_pk_bf16_f32 v140, v84, v85
	v_cvt_pk_bf16_f32 v141, v86, v87
	ds_write_b64 v212, v[140:141] offset:0
	v_cvt_pk_bf16_f32 v144, v88, v89
	v_cvt_pk_bf16_f32 v145, v90, v91
	ds_write_b64 v212, v[144:145] offset:4096
	s_nop 1
	s_waitcnt vmcnt(13)
	s_waitcnt lgkmcnt(0)
	s_barrier
	s_add_i32 m0, s46, 0xa000
	s_nop 0
	global_load_lds_dwordx4 v255, s[8:9]
	s_add_i32 m0, s46, 0xa400
	s_nop 0
	global_load_lds_dwordx4 v254, s[8:9]
	s_add_i32 m0, s47, 0xa000
	s_nop 0
	global_load_lds_dwordx4 v253, s[10:11]
	s_add_i32 m0, s48, 0xa000
	s_nop 0
	global_load_lds_dwordx4 v252, s[12:13]
	s_add_i32 m0, s48, 0xa400
	s_nop 0
	global_load_lds_dwordx4 v251, s[12:13]
	s_cmp_lt_u32 s33, 29
	s_cselect_b32 s43, 0x10000, 0
	s_add_u32 s8, s8, s43
	s_addc_u32 s9, s9, 0
	s_cmp_lt_u32 s33, 29
	s_cselect_b32 s43, 0x2000, 0
	s_add_u32 s10, s10, s43
	s_addc_u32 s11, s11, 0
	s_cmp_lt_u32 s33, 29
	s_cselect_b32 s43, 0x4000, 0
	s_add_u32 s12, s12, s43
	s_addc_u32 s13, s13, 0
	ds_read_b128 v[44:47], v217 offset:0
	ds_read_b128 v[48:51], v217 offset:2048
	ds_read_b128 v[12:15], v225 offset:0
	ds_read_b128 v[16:19], v225 offset:2048
	ds_read_b128 v[20:23], v225 offset:4096
	ds_read_b128 v[24:27], v225 offset:6144
	ds_read_b128 v[52:55], v216 offset:0
	ds_read_b128 v[56:59], v216 offset:2048
	ds_read_b128 v[28:31], v224 offset:0
	ds_read_b128 v[32:35], v224 offset:2048
	ds_read_b128 v[36:39], v224 offset:4096
	ds_read_b128 v[40:43], v224 offset:6144
	s_waitcnt vmcnt(23)
	v_pk_mul_f32 v[60:61], v[60:61], v[124:125]
	v_pk_mul_f32 v[62:63], v[62:63], v[126:127]
	v_pk_mul_f32 v[64:65], v[64:65], v[124:125]
	v_pk_mul_f32 v[66:67], v[66:67], v[126:127]
	v_pk_mul_f32 v[68:69], v[68:69], v[128:129]
	v_pk_mul_f32 v[70:71], v[70:71], v[130:131]
	v_pk_mul_f32 v[72:73], v[72:73], v[128:129]
	v_pk_mul_f32 v[74:75], v[74:75], v[130:131]
	v_pk_mul_f32 v[76:77], v[76:77], v[132:133]
	v_pk_mul_f32 v[78:79], v[78:79], v[134:135]
	v_pk_mul_f32 v[80:81], v[80:81], v[132:133]
	v_pk_mul_f32 v[82:83], v[82:83], v[134:135]
	v_pk_mul_f32 v[84:85], v[84:85], v[136:137]
	v_pk_mul_f32 v[86:87], v[86:87], v[138:139]
	v_pk_mul_f32 v[88:89], v[88:89], v[136:137]
	v_pk_mul_f32 v[90:91], v[90:91], v[138:139]
	s_waitcnt lgkmcnt(6)
	v_mfma_f32_16x16x32_bf16 v[60:63], v[12:15], v[44:47], v[60:63]
	v_mfma_f32_16x16x32_bf16 v[64:67], v[12:15], v[48:51], v[64:67]
	v_mfma_f32_16x16x32_bf16 v[68:71], v[16:19], v[44:47], v[68:71]
	v_mfma_f32_16x16x32_bf16 v[72:75], v[16:19], v[48:51], v[72:75]
	v_mfma_f32_16x16x32_bf16 v[76:79], v[20:23], v[44:47], v[76:79]
	v_mfma_f32_16x16x32_bf16 v[80:83], v[20:23], v[48:51], v[80:83]
	v_mfma_f32_16x16x32_bf16 v[84:87], v[24:27], v[44:47], v[84:87]
	v_mfma_f32_16x16x32_bf16 v[88:91], v[24:27], v[48:51], v[88:91]
	s_waitcnt lgkmcnt(0)
	v_mfma_f32_16x16x32_bf16 v[60:63], v[28:31], v[52:55], v[60:63]
	v_mfma_f32_16x16x32_bf16 v[64:67], v[28:31], v[56:59], v[64:67]
	v_mfma_f32_16x16x32_bf16 v[68:71], v[32:35], v[52:55], v[68:71]
	v_mfma_f32_16x16x32_bf16 v[72:75], v[32:35], v[56:59], v[72:75]
	v_mfma_f32_16x16x32_bf16 v[76:79], v[36:39], v[52:55], v[76:79]
	v_mfma_f32_16x16x32_bf16 v[80:83], v[36:39], v[56:59], v[80:83]
	v_mfma_f32_16x16x32_bf16 v[84:87], v[40:43], v[52:55], v[84:87]
	v_mfma_f32_16x16x32_bf16 v[88:91], v[40:43], v[56:59], v[88:91]
	s_nop 3
	global_load_dwordx4 v[124:127], v249, s[16:17] offset:0
	global_load_dwordx4 v[128:131], v249, s[16:17] offset:64
	global_load_dwordx4 v[132:135], v249, s[16:17] offset:128
	global_load_dwordx4 v[136:139], v249, s[16:17] offset:192
	s_cmp_lt_u32 s33, 28
	s_cselect_b32 s43, 0x200, 0
	s_add_u32 s16, s16, s43
	s_addc_u32 s17, s17, 0
	s_add_i32 s33, s33, 1
	s_nop 7
	s_nop 7
	v_cvt_pk_bf16_f32 v140, v60, v61
	v_cvt_pk_bf16_f32 v141, v62, v63
	ds_write_b64 v215, v[140:141] offset:12544
	v_cvt_pk_bf16_f32 v144, v64, v65
	v_cvt_pk_bf16_f32 v145, v66, v67
	ds_write_b64 v215, v[144:145] offset:16640
	s_nop 1
	v_cvt_pk_bf16_f32 v140, v68, v69
	v_cvt_pk_bf16_f32 v141, v70, v71
	ds_write_b64 v214, v[140:141] offset:12544
	v_cvt_pk_bf16_f32 v144, v72, v73
	v_cvt_pk_bf16_f32 v145, v74, v75
	ds_write_b64 v214, v[144:145] offset:16640
	s_nop 1
	v_cvt_pk_bf16_f32 v140, v76, v77
	v_cvt_pk_bf16_f32 v141, v78, v79
	ds_write_b64 v213, v[140:141] offset:12544
	v_cvt_pk_bf16_f32 v144, v80, v81
	v_cvt_pk_bf16_f32 v145, v82, v83
	ds_write_b64 v213, v[144:145] offset:16640
	s_nop 1
	v_cvt_pk_bf16_f32 v140, v84, v85
	v_cvt_pk_bf16_f32 v141, v86, v87
	ds_write_b64 v212, v[140:141] offset:12544
	v_cvt_pk_bf16_f32 v144, v88, v89
	v_cvt_pk_bf16_f32 v145, v90, v91
	ds_write_b64 v212, v[144:145] offset:16640
	s_nop 1
	s_waitcnt vmcnt(13)
	s_waitcnt lgkmcnt(0)
	s_barrier
	s_add_i32 m0, s46, 0x14000
	s_nop 0
	global_load_lds_dwordx4 v255, s[8:9]
	s_add_i32 m0, s46, 0x14400
	s_nop 0
	global_load_lds_dwordx4 v254, s[8:9]
	s_add_i32 m0, s47, 0x14000
	s_nop 0
	global_load_lds_dwordx4 v253, s[10:11]
	s_add_i32 m0, s48, 0x14000
	s_nop 0
	global_load_lds_dwordx4 v252, s[12:13]
	s_add_i32 m0, s48, 0x14400
	s_nop 0
	global_load_lds_dwordx4 v251, s[12:13]
	s_cmp_lt_u32 s33, 29
	s_cselect_b32 s43, 0x10000, 0
	s_add_u32 s8, s8, s43
	s_addc_u32 s9, s9, 0
	s_cmp_lt_u32 s33, 29
	s_cselect_b32 s43, 0x2000, 0
	s_add_u32 s10, s10, s43
	s_addc_u32 s11, s11, 0
	s_cmp_lt_u32 s33, 29
	s_cselect_b32 s43, 0x4000, 0
	s_add_u32 s12, s12, s43
	s_addc_u32 s13, s13, 0
	ds_read_b128 v[44:47], v217 offset:12288
	ds_read_b128 v[48:51], v217 offset:14336
	ds_read_b128 v[12:15], v227 offset:0
	ds_read_b128 v[16:19], v227 offset:2048
	ds_read_b128 v[20:23], v227 offset:4096
	ds_read_b128 v[24:27], v227 offset:6144
	ds_read_b128 v[52:55], v216 offset:12288
	ds_read_b128 v[56:59], v216 offset:14336
	ds_read_b128 v[28:31], v226 offset:0
	ds_read_b128 v[32:35], v226 offset:2048
	ds_read_b128 v[36:39], v226 offset:4096
	ds_read_b128 v[40:43], v226 offset:6144
	s_waitcnt vmcnt(23)
	v_pk_mul_f32 v[60:61], v[60:61], v[92:93]
	v_pk_mul_f32 v[62:63], v[62:63], v[94:95]
	v_pk_mul_f32 v[64:65], v[64:65], v[92:93]
	v_pk_mul_f32 v[66:67], v[66:67], v[94:95]
	v_pk_mul_f32 v[68:69], v[68:69], v[96:97]
	v_pk_mul_f32 v[70:71], v[70:71], v[98:99]
	v_pk_mul_f32 v[72:73], v[72:73], v[96:97]
	v_pk_mul_f32 v[74:75], v[74:75], v[98:99]
	v_pk_mul_f32 v[76:77], v[76:77], v[100:101]
	v_pk_mul_f32 v[78:79], v[78:79], v[102:103]
	v_pk_mul_f32 v[80:81], v[80:81], v[100:101]
	v_pk_mul_f32 v[82:83], v[82:83], v[102:103]
	v_pk_mul_f32 v[84:85], v[84:85], v[104:105]
	v_pk_mul_f32 v[86:87], v[86:87], v[106:107]
	v_pk_mul_f32 v[88:89], v[88:89], v[104:105]
	v_pk_mul_f32 v[90:91], v[90:91], v[106:107]
	s_waitcnt lgkmcnt(6)
	v_mfma_f32_16x16x32_bf16 v[60:63], v[12:15], v[44:47], v[60:63]
	v_mfma_f32_16x16x32_bf16 v[64:67], v[12:15], v[48:51], v[64:67]
	v_mfma_f32_16x16x32_bf16 v[68:71], v[16:19], v[44:47], v[68:71]
	v_mfma_f32_16x16x32_bf16 v[72:75], v[16:19], v[48:51], v[72:75]
	v_mfma_f32_16x16x32_bf16 v[76:79], v[20:23], v[44:47], v[76:79]
	v_mfma_f32_16x16x32_bf16 v[80:83], v[20:23], v[48:51], v[80:83]
	v_mfma_f32_16x16x32_bf16 v[84:87], v[24:27], v[44:47], v[84:87]
	v_mfma_f32_16x16x32_bf16 v[88:91], v[24:27], v[48:51], v[88:91]
	s_waitcnt lgkmcnt(0)
	v_mfma_f32_16x16x32_bf16 v[60:63], v[28:31], v[52:55], v[60:63]
	v_mfma_f32_16x16x32_bf16 v[64:67], v[28:31], v[56:59], v[64:67]
	v_mfma_f32_16x16x32_bf16 v[68:71], v[32:35], v[52:55], v[68:71]
	v_mfma_f32_16x16x32_bf16 v[72:75], v[32:35], v[56:59], v[72:75]
	v_mfma_f32_16x16x32_bf16 v[76:79], v[36:39], v[52:55], v[76:79]
	v_mfma_f32_16x16x32_bf16 v[80:83], v[36:39], v[56:59], v[80:83]
	v_mfma_f32_16x16x32_bf16 v[84:87], v[40:43], v[52:55], v[84:87]
	v_mfma_f32_16x16x32_bf16 v[88:91], v[40:43], v[56:59], v[88:91]
	s_nop 3
	global_load_dwordx4 v[92:95], v249, s[16:17] offset:0
	global_load_dwordx4 v[96:99], v249, s[16:17] offset:64
	global_load_dwordx4 v[100:103], v249, s[16:17] offset:128
	global_load_dwordx4 v[104:107], v249, s[16:17] offset:192
	s_cmp_lt_u32 s33, 28
	s_cselect_b32 s43, 0x200, 0
	s_add_u32 s16, s16, s43
	s_addc_u32 s17, s17, 0
	s_add_i32 s33, s33, 1
	s_nop 7
	s_nop 7
	v_cvt_pk_bf16_f32 v140, v60, v61
	v_cvt_pk_bf16_f32 v141, v62, v63
	ds_write_b64 v215, v[140:141] offset:0
	v_cvt_pk_bf16_f32 v144, v64, v65
	v_cvt_pk_bf16_f32 v145, v66, v67
	ds_write_b64 v215, v[144:145] offset:4096
	s_nop 1
	v_cvt_pk_bf16_f32 v140, v68, v69
	v_cvt_pk_bf16_f32 v141, v70, v71
	ds_write_b64 v214, v[140:141] offset:0
	v_cvt_pk_bf16_f32 v144, v72, v73
	v_cvt_pk_bf16_f32 v145, v74, v75
	ds_write_b64 v214, v[144:145] offset:4096
	s_nop 1
	v_cvt_pk_bf16_f32 v140, v76, v77
	v_cvt_pk_bf16_f32 v141, v78, v79
	ds_write_b64 v213, v[140:141] offset:0
	v_cvt_pk_bf16_f32 v144, v80, v81
	v_cvt_pk_bf16_f32 v145, v82, v83
	ds_write_b64 v213, v[144:145] offset:4096
	s_nop 1
	v_cvt_pk_bf16_f32 v140, v84, v85
	v_cvt_pk_bf16_f32 v141, v86, v87
	ds_write_b64 v212, v[140:141] offset:0
	v_cvt_pk_bf16_f32 v144, v88, v89
	v_cvt_pk_bf16_f32 v145, v90, v91
	ds_write_b64 v212, v[144:145] offset:4096
	s_nop 1
	s_waitcnt vmcnt(13)
	s_waitcnt lgkmcnt(0)
	s_barrier
	s_mov_b32 m0, s46
	s_nop 0
	global_load_lds_dwordx4 v255, s[8:9]
	s_add_i32 m0, s46, 0x400
	s_nop 0
	global_load_lds_dwordx4 v254, s[8:9]
	s_mov_b32 m0, s47
	s_nop 0
	global_load_lds_dwordx4 v253, s[10:11]
	s_mov_b32 m0, s48
	s_nop 0
	global_load_lds_dwordx4 v252, s[12:13]
	s_add_i32 m0, s48, 0x400
	s_nop 0
	global_load_lds_dwordx4 v251, s[12:13]
	s_cmp_lt_u32 s33, 29
	s_cselect_b32 s43, 0x10000, 0
	s_add_u32 s8, s8, s43
	s_addc_u32 s9, s9, 0
	s_cmp_lt_u32 s33, 29
	s_cselect_b32 s43, 0x2000, 0
	s_add_u32 s10, s10, s43
	s_addc_u32 s11, s11, 0
	s_cmp_lt_u32 s33, 29
	s_cselect_b32 s43, 0x4000, 0
	s_add_u32 s12, s12, s43
	s_addc_u32 s13, s13, 0
	ds_read_b128 v[44:47], v217 offset:0
	ds_read_b128 v[48:51], v217 offset:2048
	ds_read_b128 v[12:15], v227 offset:40960
	ds_read_b128 v[16:19], v227 offset:43008
	ds_read_b128 v[20:23], v227 offset:45056
	ds_read_b128 v[24:27], v227 offset:47104
	ds_read_b128 v[52:55], v216 offset:0
	ds_read_b128 v[56:59], v216 offset:2048
	ds_read_b128 v[28:31], v226 offset:40960
	ds_read_b128 v[32:35], v226 offset:43008
	ds_read_b128 v[36:39], v226 offset:45056
	ds_read_b128 v[40:43], v226 offset:47104
	s_waitcnt vmcnt(23)
	v_pk_mul_f32 v[60:61], v[60:61], v[108:109]
	v_pk_mul_f32 v[62:63], v[62:63], v[110:111]
	v_pk_mul_f32 v[64:65], v[64:65], v[108:109]
	v_pk_mul_f32 v[66:67], v[66:67], v[110:111]
	v_pk_mul_f32 v[68:69], v[68:69], v[112:113]
	v_pk_mul_f32 v[70:71], v[70:71], v[114:115]
	v_pk_mul_f32 v[72:73], v[72:73], v[112:113]
	v_pk_mul_f32 v[74:75], v[74:75], v[114:115]
	v_pk_mul_f32 v[76:77], v[76:77], v[116:117]
	v_pk_mul_f32 v[78:79], v[78:79], v[118:119]
	v_pk_mul_f32 v[80:81], v[80:81], v[116:117]
	v_pk_mul_f32 v[82:83], v[82:83], v[118:119]
	v_pk_mul_f32 v[84:85], v[84:85], v[120:121]
	v_pk_mul_f32 v[86:87], v[86:87], v[122:123]
	v_pk_mul_f32 v[88:89], v[88:89], v[120:121]
	v_pk_mul_f32 v[90:91], v[90:91], v[122:123]
	s_waitcnt lgkmcnt(6)
	v_mfma_f32_16x16x32_bf16 v[60:63], v[12:15], v[44:47], v[60:63]
	v_mfma_f32_16x16x32_bf16 v[64:67], v[12:15], v[48:51], v[64:67]
	v_mfma_f32_16x16x32_bf16 v[68:71], v[16:19], v[44:47], v[68:71]
	v_mfma_f32_16x16x32_bf16 v[72:75], v[16:19], v[48:51], v[72:75]
	v_mfma_f32_16x16x32_bf16 v[76:79], v[20:23], v[44:47], v[76:79]
	v_mfma_f32_16x16x32_bf16 v[80:83], v[20:23], v[48:51], v[80:83]
	v_mfma_f32_16x16x32_bf16 v[84:87], v[24:27], v[44:47], v[84:87]
	v_mfma_f32_16x16x32_bf16 v[88:91], v[24:27], v[48:51], v[88:91]
	s_waitcnt lgkmcnt(0)
	v_mfma_f32_16x16x32_bf16 v[60:63], v[28:31], v[52:55], v[60:63]
	v_mfma_f32_16x16x32_bf16 v[64:67], v[28:31], v[56:59], v[64:67]
	v_mfma_f32_16x16x32_bf16 v[68:71], v[32:35], v[52:55], v[68:71]
	v_mfma_f32_16x16x32_bf16 v[72:75], v[32:35], v[56:59], v[72:75]
	v_mfma_f32_16x16x32_bf16 v[76:79], v[36:39], v[52:55], v[76:79]
	v_mfma_f32_16x16x32_bf16 v[80:83], v[36:39], v[56:59], v[80:83]
	v_mfma_f32_16x16x32_bf16 v[84:87], v[40:43], v[52:55], v[84:87]
	v_mfma_f32_16x16x32_bf16 v[88:91], v[40:43], v[56:59], v[88:91]
	s_nop 3
	global_load_dwordx4 v[108:111], v249, s[16:17] offset:0
	global_load_dwordx4 v[112:115], v249, s[16:17] offset:64
	global_load_dwordx4 v[116:119], v249, s[16:17] offset:128
	global_load_dwordx4 v[120:123], v249, s[16:17] offset:192
	s_cmp_lt_u32 s33, 28
	s_cselect_b32 s43, 0x200, 0
	s_add_u32 s16, s16, s43
	s_addc_u32 s17, s17, 0
	s_add_i32 s33, s33, 1
	s_nop 7
	s_nop 7
	v_cvt_pk_bf16_f32 v140, v60, v61
	v_cvt_pk_bf16_f32 v141, v62, v63
	ds_write_b64 v215, v[140:141] offset:12544
	v_cvt_pk_bf16_f32 v144, v64, v65
	v_cvt_pk_bf16_f32 v145, v66, v67
	ds_write_b64 v215, v[144:145] offset:16640
	s_nop 1
	v_cvt_pk_bf16_f32 v140, v68, v69
	v_cvt_pk_bf16_f32 v141, v70, v71
	ds_write_b64 v214, v[140:141] offset:12544
	v_cvt_pk_bf16_f32 v144, v72, v73
	v_cvt_pk_bf16_f32 v145, v74, v75
	ds_write_b64 v214, v[144:145] offset:16640
	s_nop 1
	v_cvt_pk_bf16_f32 v140, v76, v77
	v_cvt_pk_bf16_f32 v141, v78, v79
	ds_write_b64 v213, v[140:141] offset:12544
	v_cvt_pk_bf16_f32 v144, v80, v81
	v_cvt_pk_bf16_f32 v145, v82, v83
	ds_write_b64 v213, v[144:145] offset:16640
	s_nop 1
	v_cvt_pk_bf16_f32 v140, v84, v85
	v_cvt_pk_bf16_f32 v141, v86, v87
	ds_write_b64 v212, v[140:141] offset:12544
	v_cvt_pk_bf16_f32 v144, v88, v89
	v_cvt_pk_bf16_f32 v145, v90, v91
	ds_write_b64 v212, v[144:145] offset:16640
	s_nop 1
	s_waitcnt vmcnt(13)
	s_waitcnt lgkmcnt(0)
	s_barrier
	s_add_i32 m0, s46, 0xa000
	s_nop 0
	global_load_lds_dwordx4 v255, s[8:9]
	s_add_i32 m0, s46, 0xa400
	s_nop 0
	global_load_lds_dwordx4 v254, s[8:9]
	s_add_i32 m0, s47, 0xa000
	s_nop 0
	global_load_lds_dwordx4 v253, s[10:11]
	s_add_i32 m0, s48, 0xa000
	s_nop 0
	global_load_lds_dwordx4 v252, s[12:13]
	s_add_i32 m0, s48, 0xa400
	s_nop 0
	global_load_lds_dwordx4 v251, s[12:13]
	s_cmp_lt_u32 s33, 29
	s_cselect_b32 s43, 0x10000, 0
	s_add_u32 s8, s8, s43
	s_addc_u32 s9, s9, 0
	s_cmp_lt_u32 s33, 29
	s_cselect_b32 s43, 0x2000, 0
	s_add_u32 s10, s10, s43
	s_addc_u32 s11, s11, 0
	s_cmp_lt_u32 s33, 29
	s_cselect_b32 s43, 0x4000, 0
	s_add_u32 s12, s12, s43
	s_addc_u32 s13, s13, 0
	ds_read_b128 v[44:47], v217 offset:12288
	ds_read_b128 v[48:51], v217 offset:14336
	ds_read_b128 v[12:15], v225 offset:0
	ds_read_b128 v[16:19], v225 offset:2048
	ds_read_b128 v[20:23], v225 offset:4096
	ds_read_b128 v[24:27], v225 offset:6144
	ds_read_b128 v[52:55], v216 offset:12288
	ds_read_b128 v[56:59], v216 offset:14336
	ds_read_b128 v[28:31], v224 offset:0
	ds_read_b128 v[32:35], v224 offset:2048
	ds_read_b128 v[36:39], v224 offset:4096
	ds_read_b128 v[40:43], v224 offset:6144
	s_waitcnt vmcnt(23)
	v_pk_mul_f32 v[60:61], v[60:61], v[124:125]
	v_pk_mul_f32 v[62:63], v[62:63], v[126:127]
	v_pk_mul_f32 v[64:65], v[64:65], v[124:125]
	v_pk_mul_f32 v[66:67], v[66:67], v[126:127]
	v_pk_mul_f32 v[68:69], v[68:69], v[128:129]
	v_pk_mul_f32 v[70:71], v[70:71], v[130:131]
	v_pk_mul_f32 v[72:73], v[72:73], v[128:129]
	v_pk_mul_f32 v[74:75], v[74:75], v[130:131]
	v_pk_mul_f32 v[76:77], v[76:77], v[132:133]
	v_pk_mul_f32 v[78:79], v[78:79], v[134:135]
	v_pk_mul_f32 v[80:81], v[80:81], v[132:133]
	v_pk_mul_f32 v[82:83], v[82:83], v[134:135]
	v_pk_mul_f32 v[84:85], v[84:85], v[136:137]
	v_pk_mul_f32 v[86:87], v[86:87], v[138:139]
	v_pk_mul_f32 v[88:89], v[88:89], v[136:137]
	v_pk_mul_f32 v[90:91], v[90:91], v[138:139]
	s_waitcnt lgkmcnt(6)
	v_mfma_f32_16x16x32_bf16 v[60:63], v[12:15], v[44:47], v[60:63]
	v_mfma_f32_16x16x32_bf16 v[64:67], v[12:15], v[48:51], v[64:67]
	v_mfma_f32_16x16x32_bf16 v[68:71], v[16:19], v[44:47], v[68:71]
	v_mfma_f32_16x16x32_bf16 v[72:75], v[16:19], v[48:51], v[72:75]
	v_mfma_f32_16x16x32_bf16 v[76:79], v[20:23], v[44:47], v[76:79]
	v_mfma_f32_16x16x32_bf16 v[80:83], v[20:23], v[48:51], v[80:83]
	v_mfma_f32_16x16x32_bf16 v[84:87], v[24:27], v[44:47], v[84:87]
	v_mfma_f32_16x16x32_bf16 v[88:91], v[24:27], v[48:51], v[88:91]
	s_waitcnt lgkmcnt(0)
	v_mfma_f32_16x16x32_bf16 v[60:63], v[28:31], v[52:55], v[60:63]
	v_mfma_f32_16x16x32_bf16 v[64:67], v[28:31], v[56:59], v[64:67]
	v_mfma_f32_16x16x32_bf16 v[68:71], v[32:35], v[52:55], v[68:71]
	v_mfma_f32_16x16x32_bf16 v[72:75], v[32:35], v[56:59], v[72:75]
	v_mfma_f32_16x16x32_bf16 v[76:79], v[36:39], v[52:55], v[76:79]
	v_mfma_f32_16x16x32_bf16 v[80:83], v[36:39], v[56:59], v[80:83]
	v_mfma_f32_16x16x32_bf16 v[84:87], v[40:43], v[52:55], v[84:87]
	v_mfma_f32_16x16x32_bf16 v[88:91], v[40:43], v[56:59], v[88:91]
	s_nop 3
	global_load_dwordx4 v[124:127], v249, s[16:17] offset:0
	global_load_dwordx4 v[128:131], v249, s[16:17] offset:64
	global_load_dwordx4 v[132:135], v249, s[16:17] offset:128
	global_load_dwordx4 v[136:139], v249, s[16:17] offset:192
	s_cmp_lt_u32 s33, 28
	s_cselect_b32 s43, 0x200, 0
	s_add_u32 s16, s16, s43
	s_addc_u32 s17, s17, 0
	s_add_i32 s33, s33, 1
	s_nop 7
	s_nop 7
	v_cvt_pk_bf16_f32 v140, v60, v61
	v_cvt_pk_bf16_f32 v141, v62, v63
	ds_write_b64 v215, v[140:141] offset:0
	v_cvt_pk_bf16_f32 v144, v64, v65
	v_cvt_pk_bf16_f32 v145, v66, v67
	ds_write_b64 v215, v[144:145] offset:4096
	s_nop 1
	v_cvt_pk_bf16_f32 v140, v68, v69
	v_cvt_pk_bf16_f32 v141, v70, v71
	ds_write_b64 v214, v[140:141] offset:0
	v_cvt_pk_bf16_f32 v144, v72, v73
	v_cvt_pk_bf16_f32 v145, v74, v75
	ds_write_b64 v214, v[144:145] offset:4096
	s_nop 1
	v_cvt_pk_bf16_f32 v140, v76, v77
	v_cvt_pk_bf16_f32 v141, v78, v79
	ds_write_b64 v213, v[140:141] offset:0
	v_cvt_pk_bf16_f32 v144, v80, v81
	v_cvt_pk_bf16_f32 v145, v82, v83
	ds_write_b64 v213, v[144:145] offset:4096
	s_nop 1
	v_cvt_pk_bf16_f32 v140, v84, v85
	v_cvt_pk_bf16_f32 v141, v86, v87
	ds_write_b64 v212, v[140:141] offset:0
	v_cvt_pk_bf16_f32 v144, v88, v89
	v_cvt_pk_bf16_f32 v145, v90, v91
	ds_write_b64 v212, v[144:145] offset:4096
	s_nop 1
	s_waitcnt vmcnt(13)
	s_waitcnt lgkmcnt(0)
	s_barrier
	s_cmp_lt_u32 s33, 30
	s_cbranch_scc1 .Lp3S_loop
	s_add_i32 m0, s46, 0x14000
	s_nop 0
	global_load_lds_dwordx4 v255, s[8:9]
	s_add_i32 m0, s46, 0x14400
	s_nop 0
	global_load_lds_dwordx4 v254, s[8:9]
	s_add_i32 m0, s47, 0x14000
	s_nop 0
	global_load_lds_dwordx4 v253, s[10:11]
	s_add_i32 m0, s48, 0x14000
	s_nop 0
	global_load_lds_dwordx4 v252, s[12:13]
	s_add_i32 m0, s48, 0x14400
	s_nop 0
	global_load_lds_dwordx4 v251, s[12:13]
	s_cmp_lt_u32 s33, 29
	s_cselect_b32 s43, 0x10000, 0
	s_add_u32 s8, s8, s43
	s_addc_u32 s9, s9, 0
	s_cmp_lt_u32 s33, 29
	s_cselect_b32 s43, 0x2000, 0
	s_add_u32 s10, s10, s43
	s_addc_u32 s11, s11, 0
	s_cmp_lt_u32 s33, 29
	s_cselect_b32 s43, 0x4000, 0
	s_add_u32 s12, s12, s43
	s_addc_u32 s13, s13, 0
	ds_read_b128 v[44:47], v217 offset:0
	ds_read_b128 v[48:51], v217 offset:2048
	ds_read_b128 v[12:15], v227 offset:0
	ds_read_b128 v[16:19], v227 offset:2048
	ds_read_b128 v[20:23], v227 offset:4096
	ds_read_b128 v[24:27], v227 offset:6144
	ds_read_b128 v[52:55], v216 offset:0
	ds_read_b128 v[56:59], v216 offset:2048
	ds_read_b128 v[28:31], v226 offset:0
	ds_read_b128 v[32:35], v226 offset:2048
	ds_read_b128 v[36:39], v226 offset:4096
	ds_read_b128 v[40:43], v226 offset:6144
	s_waitcnt vmcnt(23)
	v_pk_mul_f32 v[60:61], v[60:61], v[92:93]
	v_pk_mul_f32 v[62:63], v[62:63], v[94:95]
	v_pk_mul_f32 v[64:65], v[64:65], v[92:93]
	v_pk_mul_f32 v[66:67], v[66:67], v[94:95]
	v_pk_mul_f32 v[68:69], v[68:69], v[96:97]
	v_pk_mul_f32 v[70:71], v[70:71], v[98:99]
	v_pk_mul_f32 v[72:73], v[72:73], v[96:97]
	v_pk_mul_f32 v[74:75], v[74:75], v[98:99]
	v_pk_mul_f32 v[76:77], v[76:77], v[100:101]
	v_pk_mul_f32 v[78:79], v[78:79], v[102:103]
	v_pk_mul_f32 v[80:81], v[80:81], v[100:101]
	v_pk_mul_f32 v[82:83], v[82:83], v[102:103]
	v_pk_mul_f32 v[84:85], v[84:85], v[104:105]
	v_pk_mul_f32 v[86:87], v[86:87], v[106:107]
	v_pk_mul_f32 v[88:89], v[88:89], v[104:105]
	v_pk_mul_f32 v[90:91], v[90:91], v[106:107]
	s_waitcnt lgkmcnt(6)
	v_mfma_f32_16x16x32_bf16 v[60:63], v[12:15], v[44:47], v[60:63]
	v_mfma_f32_16x16x32_bf16 v[64:67], v[12:15], v[48:51], v[64:67]
	v_mfma_f32_16x16x32_bf16 v[68:71], v[16:19], v[44:47], v[68:71]
	v_mfma_f32_16x16x32_bf16 v[72:75], v[16:19], v[48:51], v[72:75]
	v_mfma_f32_16x16x32_bf16 v[76:79], v[20:23], v[44:47], v[76:79]
	v_mfma_f32_16x16x32_bf16 v[80:83], v[20:23], v[48:51], v[80:83]
	v_mfma_f32_16x16x32_bf16 v[84:87], v[24:27], v[44:47], v[84:87]
	v_mfma_f32_16x16x32_bf16 v[88:91], v[24:27], v[48:51], v[88:91]
	s_waitcnt lgkmcnt(0)
	v_mfma_f32_16x16x32_bf16 v[60:63], v[28:31], v[52:55], v[60:63]
	v_mfma_f32_16x16x32_bf16 v[64:67], v[28:31], v[56:59], v[64:67]
	v_mfma_f32_16x16x32_bf16 v[68:71], v[32:35], v[52:55], v[68:71]
	v_mfma_f32_16x16x32_bf16 v[72:75], v[32:35], v[56:59], v[72:75]
	v_mfma_f32_16x16x32_bf16 v[76:79], v[36:39], v[52:55], v[76:79]
	v_mfma_f32_16x16x32_bf16 v[80:83], v[36:39], v[56:59], v[80:83]
	v_mfma_f32_16x16x32_bf16 v[84:87], v[40:43], v[52:55], v[84:87]
	v_mfma_f32_16x16x32_bf16 v[88:91], v[40:43], v[56:59], v[88:91]
	s_nop 3
	global_load_dwordx4 v[92:95], v249, s[16:17] offset:0
	global_load_dwordx4 v[96:99], v249, s[16:17] offset:64
	global_load_dwordx4 v[100:103], v249, s[16:17] offset:128
	global_load_dwordx4 v[104:107], v249, s[16:17] offset:192
	s_cmp_lt_u32 s33, 28
	s_cselect_b32 s43, 0x200, 0
	s_add_u32 s16, s16, s43
	s_addc_u32 s17, s17, 0
	s_add_i32 s33, s33, 1
	s_nop 7
	s_nop 7
	v_cvt_pk_bf16_f32 v140, v60, v61
	v_cvt_pk_bf16_f32 v141, v62, v63
	ds_write_b64 v215, v[140:141] offset:12544
	v_cvt_pk_bf16_f32 v144, v64, v65
	v_cvt_pk_bf16_f32 v145, v66, v67
	ds_write_b64 v215, v[144:145] offset:16640
	s_nop 1
	v_cvt_pk_bf16_f32 v140, v68, v69
	v_cvt_pk_bf16_f32 v141, v70, v71
	ds_write_b64 v214, v[140:141] offset:12544
	v_cvt_pk_bf16_f32 v144, v72, v73
	v_cvt_pk_bf16_f32 v145, v74, v75
	ds_write_b64 v214, v[144:145] offset:16640
	s_nop 1
	v_cvt_pk_bf16_f32 v140, v76, v77
	v_cvt_pk_bf16_f32 v141, v78, v79
	ds_write_b64 v213, v[140:141] offset:12544
	v_cvt_pk_bf16_f32 v144, v80, v81
	v_cvt_pk_bf16_f32 v145, v82, v83
	ds_write_b64 v213, v[144:145] offset:16640
	s_nop 1
	v_cvt_pk_bf16_f32 v140, v84, v85
	v_cvt_pk_bf16_f32 v141, v86, v87
	ds_write_b64 v212, v[140:141] offset:12544
	v_cvt_pk_bf16_f32 v144, v88, v89
	v_cvt_pk_bf16_f32 v145, v90, v91
	ds_write_b64 v212, v[144:145] offset:16640
	s_nop 1
	s_waitcnt vmcnt(13)
	s_waitcnt lgkmcnt(0)
	s_barrier
; __device__ __forceinline__ void gla_scan_item(const Ctx& C, int item, LAS unsigned char* lds, int tid) {
;     ...
;     SCAN_LOAD(A, 0); SCAN_LOAD(B, 1);
; #pragma unroll
;     for (int n = 0; n < 32; n += 2) { SCAN_STEP(A, n); SCAN_STEP(B, n + 1); }
;     ...
;     float* So = C.out + OUT_GLAP + ((size_t)bh * 128 + wave * 16 + quad * 4) * 256 + sl * 32 + l15;
; #pragma unroll
;     for (int v2 = 0; v2 < 2; ++v2)
; #pragma unroll
;         for (int j = 0; j < 4; ++j) So[(size_t)j * 256 + v2 * 16] = S[v2][j];
	s_mov_b32 m0, s46
	s_nop 0
	global_load_lds_dwordx4 v255, s[8:9]
	s_add_i32 m0, s46, 0x400
	s_nop 0
	global_load_lds_dwordx4 v254, s[8:9]
	s_mov_b32 m0, s47
	s_nop 0
	global_load_lds_dwordx4 v253, s[10:11]
	s_mov_b32 m0, s48
	s_nop 0
	global_load_lds_dwordx4 v252, s[12:13]
	s_add_i32 m0, s48, 0x400
	s_nop 0
	global_load_lds_dwordx4 v251, s[12:13]
	s_cmp_lt_u32 s33, 29
	s_cselect_b32 s43, 0x10000, 0
	s_add_u32 s8, s8, s43
	s_addc_u32 s9, s9, 0
	s_cmp_lt_u32 s33, 29
	s_cselect_b32 s43, 0x2000, 0
	s_add_u32 s10, s10, s43
	s_addc_u32 s11, s11, 0
	s_cmp_lt_u32 s33, 29
	s_cselect_b32 s43, 0x4000, 0
	s_add_u32 s12, s12, s43
	s_addc_u32 s13, s13, 0
	ds_read_b128 v[44:47], v217 offset:12288
	ds_read_b128 v[48:51], v217 offset:14336
	ds_read_b128 v[12:15], v227 offset:40960
	ds_read_b128 v[16:19], v227 offset:43008
	ds_read_b128 v[20:23], v227 offset:45056
	ds_read_b128 v[24:27], v227 offset:47104
	ds_read_b128 v[52:55], v216 offset:12288
	ds_read_b128 v[56:59], v216 offset:14336
	ds_read_b128 v[28:31], v226 offset:40960
	ds_read_b128 v[32:35], v226 offset:43008
	ds_read_b128 v[36:39], v226 offset:45056
	ds_read_b128 v[40:43], v226 offset:47104
	s_waitcnt vmcnt(23)
	v_pk_mul_f32 v[60:61], v[60:61], v[108:109]
	v_pk_mul_f32 v[62:63], v[62:63], v[110:111]
	v_pk_mul_f32 v[64:65], v[64:65], v[108:109]
	v_pk_mul_f32 v[66:67], v[66:67], v[110:111]
	v_pk_mul_f32 v[68:69], v[68:69], v[112:113]
	v_pk_mul_f32 v[70:71], v[70:71], v[114:115]
	v_pk_mul_f32 v[72:73], v[72:73], v[112:113]
	v_pk_mul_f32 v[74:75], v[74:75], v[114:115]
	v_pk_mul_f32 v[76:77], v[76:77], v[116:117]
	v_pk_mul_f32 v[78:79], v[78:79], v[118:119]
	v_pk_mul_f32 v[80:81], v[80:81], v[116:117]
	v_pk_mul_f32 v[82:83], v[82:83], v[118:119]
	v_pk_mul_f32 v[84:85], v[84:85], v[120:121]
	v_pk_mul_f32 v[86:87], v[86:87], v[122:123]
	v_pk_mul_f32 v[88:89], v[88:89], v[120:121]
	v_pk_mul_f32 v[90:91], v[90:91], v[122:123]
	s_waitcnt lgkmcnt(6)
	v_mfma_f32_16x16x32_bf16 v[60:63], v[12:15], v[44:47], v[60:63]
	v_mfma_f32_16x16x32_bf16 v[64:67], v[12:15], v[48:51], v[64:67]
	v_mfma_f32_16x16x32_bf16 v[68:71], v[16:19], v[44:47], v[68:71]
	v_mfma_f32_16x16x32_bf16 v[72:75], v[16:19], v[48:51], v[72:75]
	v_mfma_f32_16x16x32_bf16 v[76:79], v[20:23], v[44:47], v[76:79]
	v_mfma_f32_16x16x32_bf16 v[80:83], v[20:23], v[48:51], v[80:83]
	v_mfma_f32_16x16x32_bf16 v[84:87], v[24:27], v[44:47], v[84:87]
	v_mfma_f32_16x16x32_bf16 v[88:91], v[24:27], v[48:51], v[88:91]
	s_waitcnt lgkmcnt(0)
	v_mfma_f32_16x16x32_bf16 v[60:63], v[28:31], v[52:55], v[60:63]
	v_mfma_f32_16x16x32_bf16 v[64:67], v[28:31], v[56:59], v[64:67]
	v_mfma_f32_16x16x32_bf16 v[68:71], v[32:35], v[52:55], v[68:71]
	v_mfma_f32_16x16x32_bf16 v[72:75], v[32:35], v[56:59], v[72:75]
	v_mfma_f32_16x16x32_bf16 v[76:79], v[36:39], v[52:55], v[76:79]
	v_mfma_f32_16x16x32_bf16 v[80:83], v[36:39], v[56:59], v[80:83]
	v_mfma_f32_16x16x32_bf16 v[84:87], v[40:43], v[52:55], v[84:87]
	v_mfma_f32_16x16x32_bf16 v[88:91], v[40:43], v[56:59], v[88:91]
	s_nop 3
	global_load_dwordx4 v[108:111], v249, s[16:17] offset:0
	global_load_dwordx4 v[112:115], v249, s[16:17] offset:64
	global_load_dwordx4 v[116:119], v249, s[16:17] offset:128
	global_load_dwordx4 v[120:123], v249, s[16:17] offset:192
	s_cmp_lt_u32 s33, 28
	s_cselect_b32 s43, 0x200, 0
	s_add_u32 s16, s16, s43
	s_addc_u32 s17, s17, 0
	s_add_i32 s33, s33, 1
	s_nop 7
	s_nop 7
	v_cvt_pk_bf16_f32 v140, v60, v61
	v_cvt_pk_bf16_f32 v141, v62, v63
	ds_write_b64 v215, v[140:141] offset:0
	v_cvt_pk_bf16_f32 v144, v64, v65
	v_cvt_pk_bf16_f32 v145, v66, v67
	ds_write_b64 v215, v[144:145] offset:4096
	s_nop 1
	v_cvt_pk_bf16_f32 v140, v68, v69
	v_cvt_pk_bf16_f32 v141, v70, v71
	ds_write_b64 v214, v[140:141] offset:0
	v_cvt_pk_bf16_f32 v144, v72, v73
	v_cvt_pk_bf16_f32 v145, v74, v75
	ds_write_b64 v214, v[144:145] offset:4096
	s_nop 1
	v_cvt_pk_bf16_f32 v140, v76, v77
	v_cvt_pk_bf16_f32 v141, v78, v79
	ds_write_b64 v213, v[140:141] offset:0
	v_cvt_pk_bf16_f32 v144, v80, v81
	v_cvt_pk_bf16_f32 v145, v82, v83
	ds_write_b64 v213, v[144:145] offset:4096
	s_nop 1
	v_cvt_pk_bf16_f32 v140, v84, v85
	v_cvt_pk_bf16_f32 v141, v86, v87
	ds_write_b64 v212, v[140:141] offset:0
	v_cvt_pk_bf16_f32 v144, v88, v89
	v_cvt_pk_bf16_f32 v145, v90, v91
	ds_write_b64 v212, v[144:145] offset:4096
	s_nop 1
	s_waitcnt vmcnt(13)
	s_waitcnt lgkmcnt(0)
	s_barrier
	s_nop 7
	global_store_dword v245, v60, s[34:35] offset:0
	global_store_dword v245, v61, s[34:35] offset:1024
	global_store_dword v245, v62, s[34:35] offset:2048
	global_store_dword v245, v63, s[34:35] offset:3072
	global_store_dword v245, v64, s[34:35] offset:64
	global_store_dword v245, v65, s[34:35] offset:1088
	global_store_dword v245, v66, s[34:35] offset:2112
	global_store_dword v245, v67, s[34:35] offset:3136
	global_store_dword v244, v68, s[34:35] offset:0
	global_store_dword v244, v69, s[34:35] offset:1024
	global_store_dword v244, v70, s[34:35] offset:2048
	global_store_dword v244, v71, s[34:35] offset:3072
	global_store_dword v244, v72, s[34:35] offset:64
	global_store_dword v244, v73, s[34:35] offset:1088
	global_store_dword v244, v74, s[34:35] offset:2112
	global_store_dword v244, v75, s[34:35] offset:3136
	global_store_dword v243, v76, s[34:35] offset:0
	global_store_dword v243, v77, s[34:35] offset:1024
	global_store_dword v243, v78, s[34:35] offset:2048
	global_store_dword v243, v79, s[34:35] offset:3072
	global_store_dword v243, v80, s[34:35] offset:64
	global_store_dword v243, v81, s[34:35] offset:1088
	global_store_dword v243, v82, s[34:35] offset:2112
	global_store_dword v243, v83, s[34:35] offset:3136
	global_store_dword v242, v84, s[34:35] offset:0
	global_store_dword v242, v85, s[34:35] offset:1024
	global_store_dword v242, v86, s[34:35] offset:2048
	global_store_dword v242, v87, s[34:35] offset:3072
	global_store_dword v242, v88, s[34:35] offset:64
	global_store_dword v242, v89, s[34:35] offset:1088
	global_store_dword v242, v90, s[34:35] offset:2112
	global_store_dword v242, v91, s[34:35] offset:3136
	s_waitcnt vmcnt(0) lgkmcnt(0)
	s_barrier
	s_add_i32 s3, s3, s42
	s_cmpk_lt_i32 s3, 0x100
	s_cbranch_scc1 .Lp3S_item
	s_branch .Lp3_done

.Lp3V_loop:
	s_add_i32 m0, s46, 0x14000
	s_nop 0
	global_load_lds_dwordx4 v255, s[8:9]
	s_add_i32 m0, s46, 0x14400
	s_nop 0
	global_load_lds_dwordx4 v254, s[8:9]
	s_add_i32 m0, s47, 0x14000
	s_nop 0
	global_load_lds_dwordx4 v253, s[10:11]
	s_add_i32 m0, s48, 0x14000
	s_nop 0
	global_load_lds_dwordx4 v252, s[12:13]
	s_add_i32 m0, s48, 0x14400
	s_nop 0
	global_load_lds_dwordx4 v251, s[12:13]
	s_cmp_lt_u32 s33, 29
	s_cselect_b32 s43, 0x10000, 0
	s_add_u32 s8, s8, s43
	s_addc_u32 s9, s9, 0
	s_cmp_lt_u32 s33, 29
	s_cselect_b32 s43, 0x2000, 0
	s_add_u32 s10, s10, s43
	s_addc_u32 s11, s11, 0
	s_cmp_lt_u32 s33, 29
	s_cselect_b32 s43, 0x4000, 0
	s_add_u32 s12, s12, s43
	s_addc_u32 s13, s13, 0
	s_waitcnt vmcnt(11)
	ds_write_b16 v211, v16 offset:12288
	ds_write_b16_d16_hi v210, v16 offset:12288
	ds_write_b16 v209, v17 offset:12288
	ds_write_b16_d16_hi v208, v17 offset:12288
	ds_write_b16 v207, v18 offset:12288
	ds_write_b16_d16_hi v206, v18 offset:12288
	ds_write_b16 v205, v19 offset:12288
	ds_write_b16_d16_hi v204, v19 offset:12288
	global_load_dwordx4 v[12:15], v250, s[14:15]
	s_cmp_lt_u32 s33, 28
	s_cselect_b32 s43, 0x100000, 0
	s_add_u32 s14, s14, s43
	s_addc_u32 s15, s15, 0
	s_add_i32 s33, s33, 1
	s_waitcnt vmcnt(7)
	s_waitcnt lgkmcnt(0)
	s_barrier
	s_mov_b32 m0, s46
	s_nop 0
	global_load_lds_dwordx4 v255, s[8:9]
	s_add_i32 m0, s46, 0x400
	s_nop 0
	global_load_lds_dwordx4 v254, s[8:9]
	s_mov_b32 m0, s47
	s_nop 0
	global_load_lds_dwordx4 v253, s[10:11]
	s_mov_b32 m0, s48
	s_nop 0
	global_load_lds_dwordx4 v252, s[12:13]
	s_add_i32 m0, s48, 0x400
	s_nop 0
	global_load_lds_dwordx4 v251, s[12:13]
	s_cmp_lt_u32 s33, 29
	s_cselect_b32 s43, 0x10000, 0
	s_add_u32 s8, s8, s43
	s_addc_u32 s9, s9, 0
	s_cmp_lt_u32 s33, 29
	s_cselect_b32 s43, 0x2000, 0
	s_add_u32 s10, s10, s43
	s_addc_u32 s11, s11, 0
	s_cmp_lt_u32 s33, 29
	s_cselect_b32 s43, 0x4000, 0
	s_add_u32 s12, s12, s43
	s_addc_u32 s13, s13, 0
	s_waitcnt vmcnt(11)
	ds_write_b16 v211, v20 offset:0
	ds_write_b16_d16_hi v210, v20 offset:0
	ds_write_b16 v209, v21 offset:0
	ds_write_b16_d16_hi v208, v21 offset:0
	ds_write_b16 v207, v22 offset:0
	ds_write_b16_d16_hi v206, v22 offset:0
	ds_write_b16 v205, v23 offset:0
	ds_write_b16_d16_hi v204, v23 offset:0
	global_load_dwordx4 v[16:19], v250, s[14:15]
	s_cmp_lt_u32 s33, 28
	s_cselect_b32 s43, 0x100000, 0
	s_add_u32 s14, s14, s43
	s_addc_u32 s15, s15, 0
	s_add_i32 s33, s33, 1
	s_waitcnt vmcnt(7)
	s_waitcnt lgkmcnt(0)
	s_barrier
	s_add_i32 m0, s46, 0xa000
	s_nop 0
	global_load_lds_dwordx4 v255, s[8:9]
	s_add_i32 m0, s46, 0xa400
	s_nop 0
	global_load_lds_dwordx4 v254, s[8:9]
	s_add_i32 m0, s47, 0xa000
	s_nop 0
	global_load_lds_dwordx4 v253, s[10:11]
	s_add_i32 m0, s48, 0xa000
	s_nop 0
	global_load_lds_dwordx4 v252, s[12:13]
	s_add_i32 m0, s48, 0xa400
	s_nop 0
	global_load_lds_dwordx4 v251, s[12:13]
	s_cmp_lt_u32 s33, 29
	s_cselect_b32 s43, 0x10000, 0
	s_add_u32 s8, s8, s43
	s_addc_u32 s9, s9, 0
	s_cmp_lt_u32 s33, 29
	s_cselect_b32 s43, 0x2000, 0
	s_add_u32 s10, s10, s43
	s_addc_u32 s11, s11, 0
	s_cmp_lt_u32 s33, 29
	s_cselect_b32 s43, 0x4000, 0
	s_add_u32 s12, s12, s43
	s_addc_u32 s13, s13, 0
	s_waitcnt vmcnt(11)
	ds_write_b16 v211, v12 offset:12288
	ds_write_b16_d16_hi v210, v12 offset:12288
	ds_write_b16 v209, v13 offset:12288
	ds_write_b16_d16_hi v208, v13 offset:12288
	ds_write_b16 v207, v14 offset:12288
	ds_write_b16_d16_hi v206, v14 offset:12288
	ds_write_b16 v205, v15 offset:12288
	ds_write_b16_d16_hi v204, v15 offset:12288
	global_load_dwordx4 v[20:23], v250, s[14:15]
	s_cmp_lt_u32 s33, 28
	s_cselect_b32 s43, 0x100000, 0
	s_add_u32 s14, s14, s43
	s_addc_u32 s15, s15, 0
	s_add_i32 s33, s33, 1
	s_waitcnt vmcnt(7)
	s_waitcnt lgkmcnt(0)
	s_barrier
	s_add_i32 m0, s46, 0x14000
	s_nop 0
	global_load_lds_dwordx4 v255, s[8:9]
	s_add_i32 m0, s46, 0x14400
	s_nop 0
	global_load_lds_dwordx4 v254, s[8:9]
	s_add_i32 m0, s47, 0x14000
	s_nop 0
	global_load_lds_dwordx4 v253, s[10:11]
	s_add_i32 m0, s48, 0x14000
	s_nop 0
	global_load_lds_dwordx4 v252, s[12:13]
	s_add_i32 m0, s48, 0x14400
	s_nop 0
	global_load_lds_dwordx4 v251, s[12:13]
	s_cmp_lt_u32 s33, 29
	s_cselect_b32 s43, 0x10000, 0
	s_add_u32 s8, s8, s43
	s_addc_u32 s9, s9, 0
	s_cmp_lt_u32 s33, 29
	s_cselect_b32 s43, 0x2000, 0
	s_add_u32 s10, s10, s43
	s_addc_u32 s11, s11, 0
	s_cmp_lt_u32 s33, 29
	s_cselect_b32 s43, 0x4000, 0
	s_add_u32 s12, s12, s43
	s_addc_u32 s13, s13, 0
	s_waitcnt vmcnt(11)
	ds_write_b16 v211, v16 offset:0
	ds_write_b16_d16_hi v210, v16 offset:0
	ds_write_b16 v209, v17 offset:0
	ds_write_b16_d16_hi v208, v17 offset:0
	ds_write_b16 v207, v18 offset:0
	ds_write_b16_d16_hi v206, v18 offset:0
	ds_write_b16 v205, v19 offset:0
	ds_write_b16_d16_hi v204, v19 offset:0
	global_load_dwordx4 v[12:15], v250, s[14:15]
	s_cmp_lt_u32 s33, 28
	s_cselect_b32 s43, 0x100000, 0
	s_add_u32 s14, s14, s43
	s_addc_u32 s15, s15, 0
	s_add_i32 s33, s33, 1
	s_waitcnt vmcnt(7)
	s_waitcnt lgkmcnt(0)
	s_barrier
	s_mov_b32 m0, s46
	s_nop 0
	global_load_lds_dwordx4 v255, s[8:9]
	s_add_i32 m0, s46, 0x400
	s_nop 0
	global_load_lds_dwordx4 v254, s[8:9]
	s_mov_b32 m0, s47
	s_nop 0
	global_load_lds_dwordx4 v253, s[10:11]
	s_mov_b32 m0, s48
	s_nop 0
	global_load_lds_dwordx4 v252, s[12:13]
	s_add_i32 m0, s48, 0x400
	s_nop 0
	global_load_lds_dwordx4 v251, s[12:13]
	s_cmp_lt_u32 s33, 29
	s_cselect_b32 s43, 0x10000, 0
	s_add_u32 s8, s8, s43
	s_addc_u32 s9, s9, 0
	s_cmp_lt_u32 s33, 29
	s_cselect_b32 s43, 0x2000, 0
	s_add_u32 s10, s10, s43
	s_addc_u32 s11, s11, 0
	s_cmp_lt_u32 s33, 29
	s_cselect_b32 s43, 0x4000, 0
	s_add_u32 s12, s12, s43
	s_addc_u32 s13, s13, 0
	s_waitcnt vmcnt(11)
	ds_write_b16 v211, v20 offset:12288
	ds_write_b16_d16_hi v210, v20 offset:12288
	ds_write_b16 v209, v21 offset:12288
	ds_write_b16_d16_hi v208, v21 offset:12288
	ds_write_b16 v207, v22 offset:12288
	ds_write_b16_d16_hi v206, v22 offset:12288
	ds_write_b16 v205, v23 offset:12288
	ds_write_b16_d16_hi v204, v23 offset:12288
	global_load_dwordx4 v[16:19], v250, s[14:15]
	s_cmp_lt_u32 s33, 28
	s_cselect_b32 s43, 0x100000, 0
	s_add_u32 s14, s14, s43
	s_addc_u32 s15, s15, 0
	s_add_i32 s33, s33, 1
	s_waitcnt vmcnt(7)
	s_waitcnt lgkmcnt(0)
	s_barrier
	s_add_i32 m0, s46, 0xa000
	s_nop 0
	global_load_lds_dwordx4 v255, s[8:9]
	s_add_i32 m0, s46, 0xa400
	s_nop 0
	global_load_lds_dwordx4 v254, s[8:9]
	s_add_i32 m0, s47, 0xa000
	s_nop 0
	global_load_lds_dwordx4 v253, s[10:11]
	s_add_i32 m0, s48, 0xa000
	s_nop 0
	global_load_lds_dwordx4 v252, s[12:13]
	s_add_i32 m0, s48, 0xa400
	s_nop 0
	global_load_lds_dwordx4 v251, s[12:13]
	s_cmp_lt_u32 s33, 29
	s_cselect_b32 s43, 0x10000, 0
	s_add_u32 s8, s8, s43
	s_addc_u32 s9, s9, 0
	s_cmp_lt_u32 s33, 29
	s_cselect_b32 s43, 0x2000, 0
	s_add_u32 s10, s10, s43
	s_addc_u32 s11, s11, 0
	s_cmp_lt_u32 s33, 29
	s_cselect_b32 s43, 0x4000, 0
	s_add_u32 s12, s12, s43
	s_addc_u32 s13, s13, 0
	s_waitcnt vmcnt(11)
	ds_write_b16 v211, v12 offset:0
	ds_write_b16_d16_hi v210, v12 offset:0
	ds_write_b16 v209, v13 offset:0
	ds_write_b16_d16_hi v208, v13 offset:0
	ds_write_b16 v207, v14 offset:0
	ds_write_b16_d16_hi v206, v14 offset:0
	ds_write_b16 v205, v15 offset:0
	ds_write_b16_d16_hi v204, v15 offset:0
	global_load_dwordx4 v[20:23], v250, s[14:15]
	s_cmp_lt_u32 s33, 28
	s_cselect_b32 s43, 0x100000, 0
	s_add_u32 s14, s14, s43
	s_addc_u32 s15, s15, 0
	s_add_i32 s33, s33, 1
	s_waitcnt vmcnt(7)
	s_waitcnt lgkmcnt(0)
	s_barrier
	s_cmp_lt_u32 s33, 30
	s_cbranch_scc1 .Lp3V_loop
	s_add_i32 m0, s46, 0x14000
	s_nop 0
	global_load_lds_dwordx4 v255, s[8:9]
	s_add_i32 m0, s46, 0x14400
	s_nop 0
	global_load_lds_dwordx4 v254, s[8:9]
	s_add_i32 m0, s47, 0x14000
	s_nop 0
	global_load_lds_dwordx4 v253, s[10:11]
	s_add_i32 m0, s48, 0x14000
	s_nop 0
	global_load_lds_dwordx4 v252, s[12:13]
	s_add_i32 m0, s48, 0x14400
	s_nop 0
	global_load_lds_dwordx4 v251, s[12:13]
	s_cmp_lt_u32 s33, 29
	s_cselect_b32 s43, 0x10000, 0
	s_add_u32 s8, s8, s43
	s_addc_u32 s9, s9, 0
	s_cmp_lt_u32 s33, 29
	s_cselect_b32 s43, 0x2000, 0
	s_add_u32 s10, s10, s43
	s_addc_u32 s11, s11, 0
	s_cmp_lt_u32 s33, 29
	s_cselect_b32 s43, 0x4000, 0
	s_add_u32 s12, s12, s43
	s_addc_u32 s13, s13, 0
	s_waitcnt vmcnt(11)
	ds_write_b16 v211, v16 offset:12288
	ds_write_b16_d16_hi v210, v16 offset:12288
	ds_write_b16 v209, v17 offset:12288
	ds_write_b16_d16_hi v208, v17 offset:12288
	ds_write_b16 v207, v18 offset:12288
	ds_write_b16_d16_hi v206, v18 offset:12288
	ds_write_b16 v205, v19 offset:12288
	ds_write_b16_d16_hi v204, v19 offset:12288
	global_load_dwordx4 v[12:15], v250, s[14:15]
	s_cmp_lt_u32 s33, 28
	s_cselect_b32 s43, 0x100000, 0
	s_add_u32 s14, s14, s43
	s_addc_u32 s15, s15, 0
	s_add_i32 s33, s33, 1
	s_waitcnt vmcnt(7)
	s_waitcnt lgkmcnt(0)
	s_barrier
	s_mov_b32 m0, s46
	s_nop 0
	global_load_lds_dwordx4 v255, s[8:9]
	s_add_i32 m0, s46, 0x400
	s_nop 0
	global_load_lds_dwordx4 v254, s[8:9]
	s_mov_b32 m0, s47
	s_nop 0
	global_load_lds_dwordx4 v253, s[10:11]
	s_mov_b32 m0, s48
	s_nop 0
	global_load_lds_dwordx4 v252, s[12:13]
	s_add_i32 m0, s48, 0x400
	s_nop 0
	global_load_lds_dwordx4 v251, s[12:13]
	s_cmp_lt_u32 s33, 29
	s_cselect_b32 s43, 0x10000, 0
	s_add_u32 s8, s8, s43
	s_addc_u32 s9, s9, 0
	s_cmp_lt_u32 s33, 29
	s_cselect_b32 s43, 0x2000, 0
	s_add_u32 s10, s10, s43
	s_addc_u32 s11, s11, 0
	s_cmp_lt_u32 s33, 29
	s_cselect_b32 s43, 0x4000, 0
	s_add_u32 s12, s12, s43
	s_addc_u32 s13, s13, 0
	s_waitcnt vmcnt(11)
	ds_write_b16 v211, v20 offset:0
	ds_write_b16_d16_hi v210, v20 offset:0
	ds_write_b16 v209, v21 offset:0
	ds_write_b16_d16_hi v208, v21 offset:0
	ds_write_b16 v207, v22 offset:0
	ds_write_b16_d16_hi v206, v22 offset:0
	ds_write_b16 v205, v23 offset:0
	ds_write_b16_d16_hi v204, v23 offset:0
	global_load_dwordx4 v[16:19], v250, s[14:15]
	s_cmp_lt_u32 s33, 28
	s_cselect_b32 s43, 0x100000, 0
	s_add_u32 s14, s14, s43
	s_addc_u32 s15, s15, 0
	s_add_i32 s33, s33, 1
	s_waitcnt vmcnt(7)
	s_waitcnt lgkmcnt(0)
	s_barrier
	s_waitcnt vmcnt(0) lgkmcnt(0)
	s_barrier
	s_add_i32 s3, s3, s42
	s_cmpk_lt_i32 s3, 0x100
	s_cbranch_scc1 .Lp3V_item
	s_branch .Lp3_done
